# diff attention loops: K/V prefetch pointers kept as per-thread 64-bit pointers (drops 8 add/addc + pads per tile pair)
# speedup vs baseline: 1.0061x; 1.0061x over previous
; #define LAS __attribute__((address_space(3)))
; #define MFMA32(a, b, c) __builtin_amdgcn_mfma_f32_32x32x16_bf16((a), (b), (c), 0, 0, 0)
; template <int DV>
; __device__ __forceinline__ void attn_pass(const bf16_t* __restrict__ Qp, const bf16_t* __restrict__ Kp, const bf16_t* __restrict__ VTp, int nt,
;                                           f32x16 (&o)[DV / 32], float& lout, LAS unsigned char* lds) {
;     ...
;     { const bf16_t* qrow = Qp + (size_t)(wid * 32 + r32) * 64 + hi * 8;
; #pragma unroll
;       for (int c = 0; c < 4; ++c) S.qr[c] = *(const bf16x8*)(qrow + c * 16); }
;     const int lrow = tid >> 3, lseg = tid & 7;
;     S.kg = Kp + (size_t)lrow * 64 + lseg * 8;
;     S.vg = VTp + (size_t)lrow * TK + lseg * 8;
;     S.kl = lrow * 144 + lseg * 16; S.vl = lrow * 144 + lseg * 16;
;     const int kvr = (r32 & ~12) | (((r32 >> 2) & 1) << 3) | (((r32 >> 3) & 1) << 2);
;     S.koff = kvr * 144 + hi * 16; S.voff = r32 * 144 + hi * 16;
;     { const u32x4 k0 = *(const u32x4*)S.kg, k1 = *(const u32x4*)(S.kg + 4096), v0 = *(const u32x4*)S.vg;
;       u32x4 v0b; if (DV == 128) v0b = *(const u32x4*)(S.vg + (size_t)64 * TK);
;       *(LAS u32x4*)(lds + AT_K0 + S.kl) = k0; *(LAS u32x4*)(lds + AT_K0 + AT_KB + S.kl) = k1; *(LAS u32x4*)(lds + AT_V0 + S.vl) = v0; if (DV == 128) *(LAS u32x4*)(lds + AT_V0 + S.vl + 64 * 144) = v0b; }
;     if (nt > 2) S.kreg = *(const u32x4*)(S.kg + (size_t)2 * 4096);
;     S.vreg0 = *(const u32x4*)(S.vg + 64); if (DV == 128) S.vreg1 = *(const u32x4*)(S.vg + (size_t)64 * TK + 64);
;     __syncthreads();
; #pragma unroll
;     for (int d = 0; d < NDB; ++d)
; #pragma unroll
;         for (int i = 0; i < 16; ++i) S.o[d][i] = 0.f;
;     S.lsum = 0.f;
;     {
;         f32x16 s0, s1;
; #pragma unroll
;         for (int i = 0; i < 16; ++i) { s0[i] = 0.f; s1[i] = 0.f; }
; #pragma unroll
;         for (int c = 0; c < 4; ++c) { const bf16x8 kf0 = lds_rd16(lds + AT_K0 + S.koff + c * 32), kf1 = lds_rd16(lds + AT_K0 + S.koff + 32 * 144 + c * 32);
;             s0 = MFMA32(kf0, S.qr[c], s0); s1 = MFMA32(kf1, S.qr[c], s1); }
; __device__ __forceinline__ void diff_unit(const Params& p, int l, int b, int h, int qb, bool ctxq, LAS unsigned char* lds) {
;     ...
;     if (ctxq) { Q1 = (const bf16_t*)(p.ws + WS_QDC) + (size_t)(b * 8 + 2 * h) * CTX * 64; Q2 = Q1 + (size_t)CTX * 64; nt = CTX / 64; yrow = (size_t)MLAT + b * CTX + wid * 32 + r32; }
.LBB0_411:
	s_andn2_b64 vcc, exec, s[0:1]
	s_cbranch_vccnz .LBB0_439
	s_add_i32 s1, s24, -4
	s_lshr_b32 s0, s1, 1
	s_and_b32 s0, s0, 0x7ffffff8
	s_add_i32 s0, s0, s30
	s_lshr_b32 s0, s0, 2
	s_bfe_u32 s2, s20, 0x20008
	s_lshl_b32 s4, s0, 3
	s_lshl_b32 s5, s2, 1
	s_or_b32 s64, s4, s5
	s_lshl_b32 s1, s1, 8
	s_and_b32 s11, s1, 0xf00
	s_lshl_b64 s[4:5], s[64:65], 19
	v_readlane_b32 s1, v252, 55
	s_add_u32 s1, s1, s4
	v_readlane_b32 s4, v252, 56
	s_addc_u32 s5, s4, s5
	s_lshl_b32 s4, s11, 7
	s_add_u32 s4, s1, s4
	s_addc_u32 s5, s5, 0
	s_mul_i32 s12, s64, 0x88000
	v_readlane_b32 s6, v252, 59
	s_mul_hi_u32 s1, s64, 0x88000
	s_add_u32 s6, s6, s12
	v_readlane_b32 s7, v252, 60
	v_readlane_b32 s16, v255, 34
	v_mov_b32_e32 v195, v218
	s_addc_u32 s7, s7, s1
	s_lshl_b32 s8, s0, 9
	s_lshl_b32 s10, s2, 7
	v_readlane_b32 s17, v255, 35
	v_mov_b32_e32 v58, v218
	s_or_b32 s2, s8, s10
	s_mul_i32 s14, s2, 0x2200
	v_readlane_b32 s8, v252, 61
	s_nop 0
	global_load_dwordx2 v[200:201], v161, s[16:17]
	s_mul_hi_u32 s13, s2, 0x2200
	v_ashrrev_i32_e32 v48, 3, v58
	v_ashrrev_i32_e32 v49, 31, v48
	v_readlane_b32 s9, v252, 62
	s_add_u32 s8, s8, s14
	v_lshlrev_b64 v[50:51], 7, v[48:49]
	v_lshlrev_b32_e32 v2, 4, v58
	s_addc_u32 s9, s9, s13
	v_lshl_add_u64 v[0:1], s[6:7], 0, v[50:51]
	v_and_b32_e32 v160, 0x70, v2
	v_lshl_add_u64 v[204:205], v[0:1], 0, v[160:161]
	v_mov_b64_e32 v[0:1], s[8:9]
	s_movk_i32 s15, 0x2200
	v_mad_i64_i32 v[0:1], s[16:17], v48, s15, v[0:1]
	s_movk_i32 s2, 0x2000
	v_lshl_add_u64 v[202:203], v[0:1], 0, v[160:161]
	v_add_co_u32_e32 v0, vcc, s2, v204
	s_mov_b32 s2, 0x88000
	s_nop 0
	v_addc_co_u32_e32 v1, vcc, 0, v205, vcc
	global_load_dwordx4 v[0:3], v[0:1], off
	s_nop 0
	global_load_dwordx4 v[4:7], v[204:205], off
	global_load_dwordx4 v[8:11], v[202:203], off
	v_add_co_u32_e32 v16, vcc, s2, v202
	v_ashrrev_i32_e32 v18, 1, v58
	s_movk_i32 s2, 0xffe0
	v_bfi_b32 v18, s2, v18, v58
	v_addc_co_u32_e32 v17, vcc, 0, v203, vcc
	v_ashrrev_i32_e32 v19, 31, v18
	global_load_dwordx4 v[12:15], v[16:17], off
	v_lshlrev_b64 v[18:19], 7, v[18:19]
	v_lshrrev_b32_e32 v20, 1, v58
	v_lshl_add_u64 v[18:19], s[4:5], 0, v[18:19]
	v_and_b32_e32 v52, 16, v20
	v_mov_b32_e32 v53, v161
	v_lshl_add_u64 v[18:19], v[18:19], 0, v[52:53]
	global_load_dwordx4 v[174:177], v[18:19], off
	global_load_dwordx4 v[170:173], v[18:19], off offset:32
	global_load_dwordx4 v[166:169], v[18:19], off offset:64
	global_load_dwordx4 v[162:165], v[18:19], off offset:96
	s_movk_i32 s2, 0x4000
	v_add_co_u32_e32 v18, vcc, s2, v204
	v_lshlrev_b32_e32 v21, 1, v58
	s_nop 0
	v_addc_co_u32_e32 v19, vcc, 0, v205, vcc
	global_load_dwordx4 v[178:181], v[18:19], off
	global_load_dwordx4 v[182:185], v[202:203], off offset:128
	global_load_dwordx4 v[186:189], v[16:17], off offset:128
	v_and_b32_e32 v22, 19, v58
	v_and_b32_e32 v23, 8, v21
	v_and_b32_e32 v24, 4, v20
	v_mad_u64_u32 v[20:21], s[16:17], v48, s92, v[160:161]
	v_or3_b32 v21, v22, v23, v24
	v_mad_u32_u24 v21, v21, s92, v52
	v_add_u32_e32 v232, 0, v20
	v_add_u32_e32 v231, 0, v21
	s_add_u32 s16, s62, s12
	s_addc_u32 s17, s63, s1
	s_mov_b32 s64, s65
	v_lshl_add_u64 v[206:207], s[16:17], 0, v[50:51]
	s_add_u32 s16, s62, s14
	s_mov_b32 s66, s65
	s_mov_b32 s67, s65
	s_mov_b32 s68, s65
	s_mov_b32 s69, s65
	s_waitcnt vmcnt(9)
	ds_write_b128 v232, v[4:7]
	ds_write_b128 v232, v[0:3] offset:9216
	s_waitcnt vmcnt(8)
	ds_write_b128 v232, v[8:11] offset:18432
	s_waitcnt vmcnt(7)
	ds_write_b128 v232, v[12:15] offset:27648
	s_waitcnt lgkmcnt(0)
	s_barrier
	ds_read_b128 v[0:3], v231
	ds_read_b128 v[4:7], v231 offset:32
	s_waitcnt vmcnt(6) lgkmcnt(1)
	v_mfma_f32_32x32x16_bf16 v[32:47], v[0:3], v[174:177], 0
	ds_read_b128 v[0:3], v231 offset:4608
	ds_read_b128 v[8:11], v231 offset:4640
	s_mov_b32 s70, s65
	s_mov_b32 s71, s65
	s_mov_b32 s72, s65
	s_mov_b32 s73, s65
	s_mov_b32 s74, s65
	s_mov_b32 s75, s65
	s_waitcnt vmcnt(5) lgkmcnt(2)
	v_mfma_f32_32x32x16_bf16 v[32:47], v[4:7], v[170:173], v[32:47]
	s_mov_b32 s76, s65
	s_mov_b32 s77, s65
	s_mov_b32 s78, s65
	s_mov_b32 s79, s65
	s_addc_u32 s17, s63, s13
	v_mov_b64_e32 v[250:251], 0x6e7
	v_mov_b32_e32 v216, 0
	s_waitcnt lgkmcnt(1)
	v_mfma_f32_32x32x16_bf16 v[16:31], v[0:3], v[174:177], 0
	ds_read_b128 v[0:3], v231 offset:64
	ds_read_b128 v[4:7], v231 offset:96
	ds_read_b128 v[54:57], v231 offset:4704
	s_mov_b32 s2, -2
	s_waitcnt vmcnt(4) lgkmcnt(2)
	v_mfma_f32_32x32x16_bf16 v[32:47], v[0:3], v[166:169], v[32:47]
	ds_read_b128 v[0:3], v231 offset:4672
	s_waitcnt lgkmcnt(0)
	s_barrier
; #define MFMA32(a, b, c) __builtin_amdgcn_mfma_f32_32x32x16_bf16((a), (b), (c), 0, 0, 0)
; template <int DV>
; __device__ __forceinline__ void attn_pass(const bf16_t* __restrict__ Qp, const bf16_t* __restrict__ Kp, const bf16_t* __restrict__ VTp, int nt,
;                                           f32x16 (&o)[DV / 32], float& lout, LAS unsigned char* lds) {
;     ...
;     S.kg = Kp + (size_t)lrow * 64 + lseg * 8;
;     S.vg = VTp + (size_t)lrow * TK + lseg * 8;
;     ...
;     __syncthreads();
; #pragma unroll
;     for (int d = 0; d < NDB; ++d)
; #pragma unroll
;         for (int i = 0; i < 16; ++i) S.o[d][i] = 0.f;
;     S.lsum = 0.f;
;     {
;         f32x16 s0, s1;
; #pragma unroll
;         for (int i = 0; i < 16; ++i) { s0[i] = 0.f; s1[i] = 0.f; }
; #pragma unroll
;         for (int c = 0; c < 4; ++c) { const bf16x8 kf0 = lds_rd16(lds + AT_K0 + S.koff + c * 32), kf1 = lds_rd16(lds + AT_K0 + S.koff + 32 * 144 + c * 32);
;             s0 = MFMA32(kf0, S.qr[c], s0); s1 = MFMA32(kf1, S.qr[c], s1); }
;         const float mx = rowmax32(s0, s1);
;         S.mrun = mx;
; #pragma unroll
;         for (int i = 0; i < 16; ++i) { S.sc0[i] = s0[i] - mx; S.sc1[i] = s1[i] - mx; S.negm[i] = -mx; }
;     }
	v_mfma_f32_32x32x16_bf16 v[16:31], v[8:11], v[170:173], v[16:31]
	v_mfma_f32_32x32x16_bf16 v[16:31], v[0:3], v[166:169], v[16:31]
	v_and_b32_e32 v0, 31, v58
	v_mul_u32_u24_e32 v49, 0x90, v0
	v_add3_u32 v230, v52, v49, 0
	s_waitcnt vmcnt(3)
	v_mfma_f32_32x32x16_bf16 v[32:47], v[4:7], v[162:165], v[32:47]
	v_mov_b64_e32 v[0:1], s[64:65]
	v_mov_b64_e32 v[14:15], s[78:79]
	v_mov_b64_e32 v[2:3], s[66:67]
	v_mov_b64_e32 v[4:5], s[68:69]
	v_mov_b64_e32 v[6:7], s[70:71]
	v_mov_b64_e32 v[8:9], s[72:73]
	v_mov_b64_e32 v[10:11], s[74:75]
	v_mfma_f32_32x32x16_bf16 v[16:31], v[54:57], v[162:165], v[16:31]
	v_max3_f32 v53, v32, v33, v16
	v_max3_f32 v54, v34, v35, v17
	v_mov_b64_e32 v[12:13], s[76:77]
	v_max3_f32 v53, v53, v18, v19
	v_max3_f32 v54, v54, v38, v39
	s_nop 0
	v_max3_f32 v53, v53, v36, v37
	v_max3_f32 v54, v54, v22, v23
	s_nop 0
	v_max3_f32 v53, v53, v20, v21
	v_max3_f32 v54, v54, v42, v43
	s_nop 0
	v_max3_f32 v53, v53, v40, v41
	v_max3_f32 v54, v54, v26, v27
	s_nop 0
	v_max3_f32 v53, v53, v24, v25
	v_max3_f32 v54, v54, v46, v47
	s_nop 0
	v_max3_f32 v53, v53, v44, v45
	v_max3_f32 v54, v54, v30, v31
	s_nop 0
	v_max3_f32 v53, v53, v28, v29
	s_nop 0
	v_max_f32_e32 v53, v53, v54
	s_nop 0
	v_mov_b32_e32 v54, v53
	s_nop 1
	v_permlane32_swap_b32_e32 v53, v54
	v_max_f32_e32 v233, v53, v54
	s_nop 0
	v_sub_f32_e32 v81, v17, v233
	v_sub_f32_e32 v80, v16, v233
	v_mov_b64_e32 v[16:17], s[16:17]
	v_xor_b32_e32 v96, 0x80000000, v233
	v_sub_f32_e32 v127, v47, v233
	v_sub_f32_e32 v126, v46, v233
	v_sub_f32_e32 v125, v45, v233
	v_sub_f32_e32 v124, v44, v233
	v_sub_f32_e32 v123, v43, v233
	v_sub_f32_e32 v122, v42, v233
	v_sub_f32_e32 v121, v41, v233
	v_sub_f32_e32 v120, v40, v233
	v_sub_f32_e32 v119, v39, v233
	v_sub_f32_e32 v118, v38, v233
	v_sub_f32_e32 v117, v37, v233
	v_sub_f32_e32 v116, v36, v233
	v_sub_f32_e32 v115, v35, v233
	v_sub_f32_e32 v114, v34, v233
	v_sub_f32_e32 v113, v33, v233
	v_sub_f32_e32 v112, v32, v233
	v_sub_f32_e32 v95, v31, v233
	v_sub_f32_e32 v94, v30, v233
	v_sub_f32_e32 v93, v29, v233
	v_sub_f32_e32 v92, v28, v233
	v_sub_f32_e32 v91, v27, v233
	v_sub_f32_e32 v90, v26, v233
	v_sub_f32_e32 v89, v25, v233
	v_sub_f32_e32 v88, v24, v233
	v_sub_f32_e32 v87, v23, v233
	v_sub_f32_e32 v86, v22, v233
	v_sub_f32_e32 v85, v21, v233
	v_sub_f32_e32 v84, v20, v233
	v_sub_f32_e32 v83, v19, v233
	v_sub_f32_e32 v82, v18, v233
	v_mad_i64_i32 v[208:209], s[16:17], v48, s15, v[16:17]
	v_mov_b64_e32 v[30:31], v[14:15]
	v_mov_b64_e32 v[46:47], v[14:15]
	v_mov_b64_e32 v[62:63], v[14:15]
	v_mov_b64_e32 v[28:29], v[12:13]
	v_mov_b64_e32 v[26:27], v[10:11]
	v_mov_b64_e32 v[24:25], v[8:9]
	v_mov_b64_e32 v[22:23], v[6:7]
	v_mov_b64_e32 v[20:21], v[4:5]
	v_mov_b64_e32 v[18:19], v[2:3]
	v_mov_b64_e32 v[16:17], v[0:1]
	v_mov_b64_e32 v[44:45], v[12:13]
	v_mov_b64_e32 v[42:43], v[10:11]
	v_mov_b64_e32 v[40:41], v[8:9]
	v_mov_b64_e32 v[38:39], v[6:7]
	v_mov_b64_e32 v[36:37], v[4:5]
	v_mov_b64_e32 v[34:35], v[2:3]
	v_mov_b64_e32 v[32:33], v[0:1]
	v_mov_b64_e32 v[60:61], v[12:13]
	v_mov_b64_e32 v[58:59], v[10:11]
	v_mov_b64_e32 v[56:57], v[8:9]
	v_mov_b64_e32 v[54:55], v[6:7]
	v_mov_b64_e32 v[52:53], v[4:5]
	v_mov_b64_e32 v[50:51], v[2:3]
	v_mov_b64_e32 v[48:49], v[0:1]
	v_mov_b32_e32 v97, v96
	v_mov_b32_e32 v98, v96
	v_mov_b32_e32 v99, v96
	v_mov_b32_e32 v100, v96
	v_mov_b32_e32 v101, v96
	v_mov_b32_e32 v102, v96
	v_mov_b32_e32 v103, v96
	v_mov_b32_e32 v104, v96
	v_mov_b32_e32 v105, v96
	v_mov_b32_e32 v106, v96
	v_mov_b32_e32 v107, v96
	v_mov_b32_e32 v108, v96
	v_mov_b32_e32 v109, v96
	v_mov_b32_e32 v110, v96
	v_mov_b32_e32 v111, v96
	s_mov_b32 s16, 0x10e06000
	s_mov_b32 s17, 0
	v_lshl_add_u64 v[206:207], v[206:207], 0, s[16:17]
	v_lshl_add_u64 v[206:207], v[206:207], 0, v[160:161]
	s_mov_b32 s16, 0x13000000
	v_lshl_add_u64 v[208:209], v[208:209], 0, s[16:17]
	v_lshl_add_u64 v[208:209], v[208:209], 0, v[160:161]
	s_mov_b32 s16, 0x88000
	s_mov_b32 s100, 0x2000
	s_mov_b32 s101, 0
	s_branch .LBB0_414

; #define LAS __attribute__((address_space(3)))
; template <int DV, int PAR, bool KW = true, bool KL = true, bool VL = true>
; __device__ __forceinline__ void attn_iter_full(AttnState<DV>& S, int t, LAS unsigned char* lds) {
;     ...
;     u32x4 pw[4]; float mxa = 0.f, mxb = 0.f, mx = 0.f; f32x16 ssum;
;     constexpr int PD = (DV == 64) ? 3 : 2; bf16x8 fr[PD + 1];
;     ...
; #pragma unroll
;     for (int i = 0; i < PD; ++i) fr[i] = AT_FRAG(i);
;     __builtin_amdgcn_sched_barrier(0);
; #pragma unroll
;     for (int i = 0; i < NS; ++i) {
;         if (i + PD < NS) fr[(i + PD) % (PD + 1)] = AT_FRAG(i + PD);
;         if (i == 3) {
;             if (KW) *(LAS u32x4*)(lds + AT_K0 + PAR * AT_KB + S.kl) = S.kreg;
;             LAS unsigned char* W = lds + AT_V0 + (PAR ^ 1) * AT_VB + S.vl; *(LAS u32x4*)W = S.vreg0; if (DV == 128) *(LAS u32x4*)(W + 64 * 144) = S.vreg1; }
;         if (i == 5) { if (KL) S.kreg = *(const u32x4*)(S.kg + (size_t)(t + 3) * 4096);
;             if (VL) { S.vreg0 = *(const u32x4*)(S.vg + (t + 2) * 64); if (DV == 128) S.vreg1 = *(const u32x4*)(S.vg + (size_t)64 * TK + (t + 2) * 64); } }
;         if (i < 8) { if (i & 1) sn1 = MFMA32(fr[i % (PD + 1)], S.qr[i >> 1], sn1); else sn0 = MFMA32(fr[i % (PD + 1)], S.qr[i >> 1], sn0); }
;         else { const int j = i - 8; S.o[j % NDB] = MFMA32(fr[i % (PD + 1)], __builtin_bit_cast(bf16x8, pw[j / NDB]), S.o[j % NDB]); }
; #pragma unroll
;         for (int u = 0; u < NU; ++u) {
;             if (u * NS / NU != i) continue;
;             if (u < 20) {
;                 const int q = u / 5, r = u % 5;
;                 if (r < 4) { const int e = 8 * q + 2 * r;
;                     if (e < 16) { C0[e] = fast_exp2(C0[e]); C0[e + 1] = fast_exp2(C0[e + 1]); }
;                     else { C1[e - 16] = fast_exp2(C1[e - 16]); C1[e - 15] = fast_exp2(C1[e - 15]); } }
;                 else { if (q < 2) { const int b0 = 8 * q; pw[q].x = pk2(C0[b0], C0[b0 + 1]); pw[q].y = pk2(C0[b0 + 2], C0[b0 + 3]); pw[q].z = pk2(C0[b0 + 4], C0[b0 + 5]); pw[q].w = pk2(C0[b0 + 6], C0[b0 + 7]); }
;                        else { const int b0 = 8 * (q - 2); pw[q].x = pk2(C1[b0], C1[b0 + 1]); pw[q].y = pk2(C1[b0 + 2], C1[b0 + 3]); pw[q].z = pk2(C1[b0 + 4], C1[b0 + 5]); pw[q].w = pk2(C1[b0 + 6], C1[b0 + 7]); } }
;             } else if (u == 20) { ssum = C0 + C1; }
.LBB0_414:
	ds_read_b128 v[64:67], v231 offset:9216
	ds_read_b128 v[68:71], v231 offset:13824
	s_waitcnt lgkmcnt(1)
	v_mfma_f32_32x32x16_bf16 v[144:159], v[64:67], v[174:177], v[96:111]
	ds_read_b128 v[72:75], v231 offset:9248
	v_exp_f32_e32 v64, v114
	v_exp_f32_e32 v66, v112
	v_exp_f32_e32 v67, v113
	v_exp_f32_e32 v65, v115
	s_waitcnt lgkmcnt(1)
	v_mfma_f32_32x32x16_bf16 v[128:143], v[68:71], v[174:177], v[96:111]
	ds_read_b128 v[76:79], v231 offset:13856
	v_exp_f32_e32 v68, v116
	v_exp_f32_e32 v69, v117
	s_waitcnt lgkmcnt(1)
	v_mfma_f32_32x32x16_bf16 v[144:159], v[72:75], v[170:173], v[144:159]
	ds_read_b128 v[112:115], v231 offset:9280
	v_exp_f32_e32 v70, v118
	v_exp_f32_e32 v71, v119
	s_waitcnt lgkmcnt(1)
	v_mfma_f32_32x32x16_bf16 v[128:143], v[76:79], v[170:173], v[128:143]
	ds_read_b128 v[116:119], v231 offset:13888
	s_waitcnt vmcnt(2)
	ds_write_b128 v232, v[178:181]
	s_waitcnt vmcnt(1)
	ds_write_b128 v232, v[182:185] offset:36864
	s_waitcnt vmcnt(0)
	ds_write_b128 v232, v[186:189] offset:46080
	v_cvt_pk_bf16_f32 v74, v66, v67
	v_cvt_pk_bf16_f32 v75, v64, v65
	v_cvt_pk_bf16_f32 v76, v68, v69
	v_cvt_pk_bf16_f32 v77, v70, v71
	s_waitcnt lgkmcnt(4)
	v_mfma_f32_32x32x16_bf16 v[144:159], v[112:115], v[166:169], v[144:159]
	ds_read_b128 v[234:237], v231 offset:9312
	v_exp_f32_e32 v72, v120
	v_exp_f32_e32 v73, v121
	ds_read_b128 v[112:115], v231 offset:13920
	global_load_dwordx4 v[178:181], v[206:207], off
	global_load_dwordx4 v[182:185], v[208:209], off offset:256
	v_lshl_add_u64 v[214:215], v[208:209], 0, s[16:17]
	global_load_dwordx4 v[186:189], v[214:215], off offset:256
	s_waitcnt lgkmcnt(5)
	v_mfma_f32_32x32x16_bf16 v[128:143], v[116:119], v[166:169], v[128:143]
	v_exp_f32_e32 v190, v122
	v_exp_f32_e32 v191, v123
	s_waitcnt lgkmcnt(1)
	v_mfma_f32_32x32x16_bf16 v[144:159], v[234:237], v[162:165], v[144:159]
	ds_read_b128 v[116:119], v230 offset:18432
	v_exp_f32_e32 v124, v124
	v_exp_f32_e32 v125, v125
	s_waitcnt lgkmcnt(1)
	v_mfma_f32_32x32x16_bf16 v[128:143], v[112:115], v[162:165], v[128:143]
	ds_read_b128 v[120:123], v230 offset:23040
	v_exp_f32_e32 v126, v126
	v_exp_f32_e32 v127, v127
	s_waitcnt lgkmcnt(1)
	v_mfma_f32_32x32x16_bf16 v[48:63], v[116:119], v[74:77], v[48:63]
	ds_read_b128 v[112:115], v230 offset:27648
	v_cvt_pk_bf16_f32 v116, v72, v73
	v_cvt_pk_bf16_f32 v117, v190, v191
	v_cvt_pk_bf16_f32 v118, v124, v125
	v_cvt_pk_bf16_f32 v119, v126, v127
	v_exp_f32_e32 v192, v80
	v_exp_f32_e32 v193, v81
	s_waitcnt lgkmcnt(1)
	v_mfma_f32_32x32x16_bf16 v[32:47], v[120:123], v[74:77], v[32:47]
	ds_read_b128 v[78:81], v230 offset:32256
	v_exp_f32_e32 v196, v82
	v_exp_f32_e32 v197, v83
	s_waitcnt lgkmcnt(1)
	v_mfma_f32_32x32x16_bf16 v[16:31], v[112:115], v[74:77], v[16:31]
	ds_read_b128 v[120:123], v230 offset:18464
	v_exp_f32_e32 v198, v84
	v_exp_f32_e32 v199, v85
	s_waitcnt lgkmcnt(1)
	v_mfma_f32_32x32x16_bf16 v[0:15], v[78:81], v[74:77], v[0:15]
	ds_read_b128 v[82:85], v230 offset:23072
	v_exp_f32_e32 v234, v86
	v_exp_f32_e32 v235, v87
	s_waitcnt lgkmcnt(1)
	v_mfma_f32_32x32x16_bf16 v[48:63], v[120:123], v[116:119], v[48:63]
	ds_read_b128 v[74:77], v230 offset:27680
	v_cvt_pk_bf16_f32 v78, v192, v193
	v_cvt_pk_bf16_f32 v79, v196, v197
	v_cvt_pk_bf16_f32 v80, v198, v199
	v_cvt_pk_bf16_f32 v81, v234, v235
	s_waitcnt lgkmcnt(1)
	v_mfma_f32_32x32x16_bf16 v[32:47], v[82:85], v[116:119], v[32:47]
	ds_read_b128 v[112:115], v230 offset:32288
	v_exp_f32_e32 v120, v88
	v_exp_f32_e32 v121, v89
	s_waitcnt lgkmcnt(1)
	v_mfma_f32_32x32x16_bf16 v[16:31], v[74:77], v[116:119], v[16:31]
	ds_read_b128 v[82:85], v230 offset:18496
	v_exp_f32_e32 v122, v90
	v_exp_f32_e32 v123, v91
	s_waitcnt lgkmcnt(1)
	v_mfma_f32_32x32x16_bf16 v[0:15], v[112:115], v[116:119], v[0:15]
	ds_read_b128 v[74:77], v230 offset:23104
	v_exp_f32_e32 v112, v92
	v_exp_f32_e32 v113, v93
	s_waitcnt lgkmcnt(1)
	v_mfma_f32_32x32x16_bf16 v[48:63], v[82:85], v[78:81], v[48:63]
	ds_read_b128 v[86:89], v230 offset:27712
	v_exp_f32_e32 v94, v94
	v_exp_f32_e32 v95, v95
	v_cvt_pk_bf16_f32 v82, v120, v121
	v_cvt_pk_bf16_f32 v83, v122, v123
	v_cvt_pk_bf16_f32 v84, v112, v113
	v_cvt_pk_bf16_f32 v85, v94, v95
	s_waitcnt lgkmcnt(1)
	v_mfma_f32_32x32x16_bf16 v[32:47], v[74:77], v[78:81], v[32:47]
	ds_read_b128 v[90:93], v230 offset:32320
	v_add_f32_e64 v74, v112, v124
	v_add_f32_e64 v75, v113, v125
	v_add_f32_e64 v76, v94, v126
	v_add_f32_e64 v77, v95, v127
	v_pk_add_f32 v[94:95], v[122:123], v[190:191]
	v_pk_add_f32 v[72:73], v[120:121], v[72:73]
	v_pk_add_f32 v[68:69], v[198:199], v[68:69]
	v_pk_add_f32 v[112:113], v[192:193], v[66:67]
	v_pk_add_f32 v[70:71], v[234:235], v[70:71]
	v_pk_add_f32 v[114:115], v[196:197], v[64:65]
	s_waitcnt lgkmcnt(1)
	v_mfma_f32_32x32x16_bf16 v[16:31], v[86:89], v[78:81], v[16:31]
	v_add_f32_e64 v70, v114, v70
	v_add_f32_e64 v71, v115, v71
	v_add_f32_e64 v68, v112, v68
	v_add_f32_e64 v69, v113, v69
	v_add_f32_e64 v70, v94, v70
	v_add_f32_e64 v71, v95, v71
	v_pk_add_f32 v[68:69], v[72:73], v[68:69]
	ds_read_b128 v[64:67], v230 offset:18528
	v_pk_add_f32 v[70:71], v[76:77], v[70:71]
	v_pk_add_f32 v[68:69], v[74:75], v[68:69]
	s_nop 0
	v_pk_mov_b32 v[72:73], v[68:69], v[70:71] op_sel:[1,0]
	v_mov_b32_e32 v69, v71
	v_pk_add_f32 v[68:69], v[72:73], v[68:69]
	s_nop 0
	v_add_f32_e32 v68, v68, v69
	v_add_f32_e32 v234, v216, v68
	s_waitcnt lgkmcnt(1)
	v_mfma_f32_32x32x16_bf16 v[0:15], v[90:93], v[78:81], v[0:15]
	ds_read_b128 v[68:71], v230 offset:23136
	v_max3_f32 v72, v144, v145, v128
	v_max3_f32 v76, v146, v147, v129
	v_max3_f32 v77, v72, v130, v131
	s_waitcnt lgkmcnt(1)
	v_mfma_f32_32x32x16_bf16 v[48:63], v[64:67], v[82:85], v[48:63]
	ds_read_b128 v[72:75], v230 offset:27744
	v_max3_f32 v64, v77, v148, v149
	v_max3_f32 v65, v76, v150, v151
	v_max3_f32 v76, v64, v132, v133
	v_max3_f32 v77, v65, v134, v135
	s_waitcnt lgkmcnt(1)
	v_mfma_f32_32x32x16_bf16 v[32:47], v[68:71], v[82:85], v[32:47]
	ds_read_b128 v[64:67], v230 offset:32352
	v_max3_f32 v68, v76, v152, v153
	v_max3_f32 v69, v77, v154, v155
	v_max3_f32 v68, v68, v136, v137
	v_max3_f32 v69, v69, v138, v139
	s_waitcnt lgkmcnt(1)
	v_mfma_f32_32x32x16_bf16 v[16:31], v[72:75], v[82:85], v[16:31]
	v_max3_f32 v68, v68, v156, v157
	v_max3_f32 v69, v69, v158, v159
	v_max3_f32 v68, v68, v140, v141
	v_max3_f32 v69, v69, v142, v143
	s_waitcnt lgkmcnt(0)
	v_mfma_f32_32x32x16_bf16 v[0:15], v[64:67], v[82:85], v[0:15]
	v_max_f32_e32 v64, v68, v69
	v_mov_b32_e32 v65, v64
	s_nop 1
	v_permlane32_swap_b32_e32 v64, v65
	v_max_f32_e32 v64, v64, v65
	s_nop 0
	v_cmp_lt_f32_e32 vcc, s3, v64
	s_cbranch_vccz .LBB0_416
; __device__ __forceinline__ float fast_exp2(float x) { return __builtin_amdgcn_exp2f(x); }
; template <int DV, int PAR, bool KW = true, bool KL = true, bool VL = true>
; __device__ __forceinline__ void attn_iter_full(AttnState<DV>& S, int t, LAS unsigned char* lds) {
;     ...
;     if (__any(mx > 8.0f)) {
;         const float dl = fmaxf(mx, 0.f), alpha = fast_exp2(-dl);
;         S.mrun += dl; S.lsum *= alpha;
; #pragma unroll
;         for (int i = 0; i < 16; ++i) { sn0[i] -= dl; sn1[i] -= dl; S.negm[i] = -S.mrun; }
; #pragma unroll
;         for (int d = 0; d < NDB; ++d)
; #pragma unroll
;             for (int i = 0; i < 16; ++i) S.o[d][i] *= alpha;
;     }
	v_max_f32_e32 v64, v64, v64
	v_max_f32_e32 v66, 0, v64
	v_exp_f32_e64 v68, -v66
	v_add_f32_e32 v233, v233, v66
	v_xor_b32_e32 v64, 0x80000000, v233
	v_pk_add_f32 v[144:145], v[144:145], v[66:67] op_sel_hi:[1,0] neg_lo:[0,1] neg_hi:[0,1]
	v_mul_f32_e32 v234, v234, v68
	v_pk_add_f32 v[128:129], v[128:129], v[66:67] op_sel_hi:[1,0] neg_lo:[0,1] neg_hi:[0,1]
	v_pk_add_f32 v[146:147], v[146:147], v[66:67] op_sel_hi:[1,0] neg_lo:[0,1] neg_hi:[0,1]
	v_pk_add_f32 v[130:131], v[130:131], v[66:67] op_sel_hi:[1,0] neg_lo:[0,1] neg_hi:[0,1]
	v_pk_add_f32 v[148:149], v[148:149], v[66:67] op_sel_hi:[1,0] neg_lo:[0,1] neg_hi:[0,1]
	v_pk_add_f32 v[132:133], v[132:133], v[66:67] op_sel_hi:[1,0] neg_lo:[0,1] neg_hi:[0,1]
	v_pk_add_f32 v[150:151], v[150:151], v[66:67] op_sel_hi:[1,0] neg_lo:[0,1] neg_hi:[0,1]
	v_pk_add_f32 v[134:135], v[134:135], v[66:67] op_sel_hi:[1,0] neg_lo:[0,1] neg_hi:[0,1]
	v_pk_add_f32 v[152:153], v[152:153], v[66:67] op_sel_hi:[1,0] neg_lo:[0,1] neg_hi:[0,1]
	v_pk_add_f32 v[136:137], v[136:137], v[66:67] op_sel_hi:[1,0] neg_lo:[0,1] neg_hi:[0,1]
	v_pk_add_f32 v[154:155], v[154:155], v[66:67] op_sel_hi:[1,0] neg_lo:[0,1] neg_hi:[0,1]
	v_pk_add_f32 v[138:139], v[138:139], v[66:67] op_sel_hi:[1,0] neg_lo:[0,1] neg_hi:[0,1]
	v_pk_add_f32 v[156:157], v[156:157], v[66:67] op_sel_hi:[1,0] neg_lo:[0,1] neg_hi:[0,1]
	v_pk_add_f32 v[140:141], v[140:141], v[66:67] op_sel_hi:[1,0] neg_lo:[0,1] neg_hi:[0,1]
	v_pk_add_f32 v[158:159], v[158:159], v[66:67] op_sel_hi:[1,0] neg_lo:[0,1] neg_hi:[0,1]
	v_pk_add_f32 v[142:143], v[142:143], v[66:67] op_sel_hi:[1,0] neg_lo:[0,1] neg_hi:[0,1]
	v_pk_mul_f32 v[62:63], v[62:63], v[68:69] op_sel_hi:[1,0]
	v_pk_mul_f32 v[60:61], v[60:61], v[68:69] op_sel_hi:[1,0]
	v_pk_mul_f32 v[58:59], v[58:59], v[68:69] op_sel_hi:[1,0]
	v_pk_mul_f32 v[56:57], v[56:57], v[68:69] op_sel_hi:[1,0]
	v_pk_mul_f32 v[54:55], v[54:55], v[68:69] op_sel_hi:[1,0]
	v_pk_mul_f32 v[52:53], v[52:53], v[68:69] op_sel_hi:[1,0]
	v_pk_mul_f32 v[50:51], v[50:51], v[68:69] op_sel_hi:[1,0]
	v_pk_mul_f32 v[48:49], v[48:49], v[68:69] op_sel_hi:[1,0]
	v_pk_mul_f32 v[46:47], v[46:47], v[68:69] op_sel_hi:[1,0]
	v_pk_mul_f32 v[44:45], v[44:45], v[68:69] op_sel_hi:[1,0]
	v_pk_mul_f32 v[42:43], v[42:43], v[68:69] op_sel_hi:[1,0]
	v_pk_mul_f32 v[40:41], v[40:41], v[68:69] op_sel_hi:[1,0]
	v_pk_mul_f32 v[38:39], v[38:39], v[68:69] op_sel_hi:[1,0]
	v_pk_mul_f32 v[36:37], v[36:37], v[68:69] op_sel_hi:[1,0]
	v_pk_mul_f32 v[34:35], v[34:35], v[68:69] op_sel_hi:[1,0]
	v_pk_mul_f32 v[32:33], v[32:33], v[68:69] op_sel_hi:[1,0]
	v_pk_mul_f32 v[30:31], v[30:31], v[68:69] op_sel_hi:[1,0]
	v_pk_mul_f32 v[28:29], v[28:29], v[68:69] op_sel_hi:[1,0]
	v_pk_mul_f32 v[26:27], v[26:27], v[68:69] op_sel_hi:[1,0]
	v_pk_mul_f32 v[24:25], v[24:25], v[68:69] op_sel_hi:[1,0]
	v_pk_mul_f32 v[22:23], v[22:23], v[68:69] op_sel_hi:[1,0]
	v_pk_mul_f32 v[20:21], v[20:21], v[68:69] op_sel_hi:[1,0]
	v_pk_mul_f32 v[18:19], v[18:19], v[68:69] op_sel_hi:[1,0]
	v_pk_mul_f32 v[16:17], v[16:17], v[68:69] op_sel_hi:[1,0]
	v_pk_mul_f32 v[14:15], v[14:15], v[68:69] op_sel_hi:[1,0]
	v_pk_mul_f32 v[12:13], v[12:13], v[68:69] op_sel_hi:[1,0]
	v_pk_mul_f32 v[10:11], v[10:11], v[68:69] op_sel_hi:[1,0]
	v_pk_mul_f32 v[8:9], v[8:9], v[68:69] op_sel_hi:[1,0]
	v_pk_mul_f32 v[6:7], v[6:7], v[68:69] op_sel_hi:[1,0]
	v_pk_mul_f32 v[4:5], v[4:5], v[68:69] op_sel_hi:[1,0]
	v_pk_mul_f32 v[2:3], v[2:3], v[68:69] op_sel_hi:[1,0]
	v_pk_mul_f32 v[0:1], v[0:1], v[68:69] op_sel_hi:[1,0]
	v_mov_b32_e32 v65, v64
	v_mov_b32_e32 v66, v64
	v_mov_b32_e32 v67, v64
	v_mov_b32_e32 v68, v64
	v_mov_b32_e32 v69, v64
	v_mov_b32_e32 v70, v64
	v_mov_b32_e32 v71, v64
	v_mov_b32_e32 v72, v64
	v_mov_b32_e32 v73, v64
	v_mov_b32_e32 v74, v64
	v_mov_b32_e32 v75, v64
	v_mov_b32_e32 v76, v64
	v_mov_b32_e32 v77, v64
	v_mov_b32_e32 v78, v64
	v_mov_b32_e32 v79, v64
	v_mov_b32_e32 v96, v64
	v_mov_b32_e32 v97, v64
	v_mov_b32_e32 v98, v64
	v_mov_b32_e32 v99, v64
	v_mov_b32_e32 v100, v64
	v_mov_b32_e32 v101, v64
	v_mov_b32_e32 v102, v64
	v_mov_b32_e32 v103, v64
	v_mov_b32_e32 v104, v64
	v_mov_b32_e32 v105, v64
	v_mov_b32_e32 v106, v64
	v_mov_b32_e32 v107, v64
	v_mov_b32_e32 v108, v64
	v_mov_b32_e32 v109, v64
	v_mov_b32_e32 v110, v64
	v_mov_b32_e32 v111, v64
	s_branch .LBB0_417
; #define LAS __attribute__((address_space(3)))
; template <int DV, int PAR, bool KW = true, bool KL = true, bool VL = true>
; __device__ __forceinline__ void attn_iter_full(AttnState<DV>& S, int t, LAS unsigned char* lds) {
;     ...
;     u32x4 pw[4]; float mxa = 0.f, mxb = 0.f, mx = 0.f; f32x16 ssum;
;     constexpr int PD = (DV == 64) ? 3 : 2; bf16x8 fr[PD + 1];
;     ...
; #pragma unroll
;     for (int i = 0; i < PD; ++i) fr[i] = AT_FRAG(i);
;     __builtin_amdgcn_sched_barrier(0);
; #pragma unroll
;     for (int i = 0; i < NS; ++i) {
;         if (i + PD < NS) fr[(i + PD) % (PD + 1)] = AT_FRAG(i + PD);
;         if (i == 3) {
;             if (KW) *(LAS u32x4*)(lds + AT_K0 + PAR * AT_KB + S.kl) = S.kreg;
;             LAS unsigned char* W = lds + AT_V0 + (PAR ^ 1) * AT_VB + S.vl; *(LAS u32x4*)W = S.vreg0; if (DV == 128) *(LAS u32x4*)(W + 64 * 144) = S.vreg1; }
;         if (i == 5) { if (KL) S.kreg = *(const u32x4*)(S.kg + (size_t)(t + 3) * 4096);
;             if (VL) { S.vreg0 = *(const u32x4*)(S.vg + (t + 2) * 64); if (DV == 128) S.vreg1 = *(const u32x4*)(S.vg + (size_t)64 * TK + (t + 2) * 64); } }
;         if (i < 8) { if (i & 1) sn1 = MFMA32(fr[i % (PD + 1)], S.qr[i >> 1], sn1); else sn0 = MFMA32(fr[i % (PD + 1)], S.qr[i >> 1], sn0); }
;         else { const int j = i - 8; S.o[j % NDB] = MFMA32(fr[i % (PD + 1)], __builtin_bit_cast(bf16x8, pw[j / NDB]), S.o[j % NDB]); }
; #pragma unroll
;         for (int u = 0; u < NU; ++u) {
;             if (u * NS / NU != i) continue;
;             if (u < 20) {
;                 const int q = u / 5, r = u % 5;
;                 if (r < 4) { const int e = 8 * q + 2 * r;
;                     if (e < 16) { C0[e] = fast_exp2(C0[e]); C0[e + 1] = fast_exp2(C0[e + 1]); }
;                     else { C1[e - 16] = fast_exp2(C1[e - 16]); C1[e - 15] = fast_exp2(C1[e - 15]); } }
;                 else { if (q < 2) { const int b0 = 8 * q; pw[q].x = pk2(C0[b0], C0[b0 + 1]); pw[q].y = pk2(C0[b0 + 2], C0[b0 + 3]); pw[q].z = pk2(C0[b0 + 4], C0[b0 + 5]); pw[q].w = pk2(C0[b0 + 6], C0[b0 + 7]); }
;                        else { const int b0 = 8 * (q - 2); pw[q].x = pk2(C1[b0], C1[b0 + 1]); pw[q].y = pk2(C1[b0 + 2], C1[b0 + 3]); pw[q].z = pk2(C1[b0 + 4], C1[b0 + 5]); pw[q].w = pk2(C1[b0 + 6], C1[b0 + 7]); } }
;             } else if (u == 20) { ssum = C0 + C1; }
.LBB0_416:
.LBB0_417:
	s_barrier
	ds_read_b128 v[80:83], v231
	ds_read_b128 v[242:245], v231 offset:4608
	s_waitcnt lgkmcnt(1)
	v_mfma_f32_32x32x16_bf16 v[112:127], v[80:83], v[174:177], v[96:111]
	ds_read_b128 v[246:249], v231 offset:32
	v_exp_f32_e32 v216, v144
	v_exp_f32_e32 v217, v145
	v_exp_f32_e32 v144, v146
	v_exp_f32_e32 v145, v147
	s_waitcnt lgkmcnt(1)
	v_mfma_f32_32x32x16_bf16 v[80:95], v[242:245], v[174:177], v[96:111]
	ds_read_b128 v[190:193], v231 offset:4640
	v_exp_f32_e32 v146, v148
	v_exp_f32_e32 v147, v149
	s_waitcnt lgkmcnt(1)
	v_mfma_f32_32x32x16_bf16 v[112:127], v[246:249], v[170:173], v[112:127]
	ds_read_b128 v[242:245], v231 offset:64
	v_exp_f32_e32 v148, v150
	v_exp_f32_e32 v149, v151
	s_waitcnt lgkmcnt(1)
	v_mfma_f32_32x32x16_bf16 v[80:95], v[190:193], v[170:173], v[80:95]
	ds_read_b128 v[246:249], v231 offset:4672
	s_waitcnt vmcnt(2)
	ds_write_b128 v232, v[178:181] offset:9216
	s_waitcnt vmcnt(1)
	ds_write_b128 v232, v[182:185] offset:18432
	s_waitcnt vmcnt(0)
	ds_write_b128 v232, v[186:189] offset:27648
	v_cvt_pk_bf16_f32 v196, v216, v217
	v_cvt_pk_bf16_f32 v197, v144, v145
	v_cvt_pk_bf16_f32 v198, v146, v147
	v_cvt_pk_bf16_f32 v199, v148, v149
	s_waitcnt lgkmcnt(4)
	v_mfma_f32_32x32x16_bf16 v[112:127], v[242:245], v[166:169], v[112:127]
	ds_read_b128 v[190:193], v231 offset:96
	v_exp_f32_e32 v150, v152
	v_exp_f32_e32 v151, v153
	v_lshl_add_u64 v[152:153], v[206:207], 0, s[100:101]
	ds_read_b128 v[242:245], v231 offset:4704
	global_load_dwordx4 v[178:181], v[152:153], off
	global_load_dwordx4 v[182:185], v[208:209], off offset:384
	global_load_dwordx4 v[186:189], v[214:215], off offset:384
	s_waitcnt lgkmcnt(5)
	v_mfma_f32_32x32x16_bf16 v[80:95], v[246:249], v[166:169], v[80:95]
	v_exp_f32_e32 v214, v154
	v_exp_f32_e32 v215, v155
	s_waitcnt lgkmcnt(1)
	v_mfma_f32_32x32x16_bf16 v[112:127], v[190:193], v[162:165], v[112:127]
	ds_read_b128 v[152:155], v230 offset:36864
	v_exp_f32_e32 v236, v156
	v_exp_f32_e32 v237, v157
	s_waitcnt lgkmcnt(1)
	v_mfma_f32_32x32x16_bf16 v[80:95], v[242:245], v[162:165], v[80:95]
	ds_read_b128 v[190:193], v230 offset:41472
	v_exp_f32_e32 v242, v158
	v_exp_f32_e32 v243, v159
	s_waitcnt lgkmcnt(1)
	v_mfma_f32_32x32x16_bf16 v[48:63], v[152:155], v[196:199], v[48:63]
	ds_read_b128 v[156:159], v230 offset:46080
	v_cvt_pk_bf16_f32 v152, v150, v151
	v_cvt_pk_bf16_f32 v153, v214, v215
	v_cvt_pk_bf16_f32 v154, v236, v237
	v_cvt_pk_bf16_f32 v155, v242, v243
	v_exp_f32_e32 v244, v128
	v_exp_f32_e32 v245, v129
	s_waitcnt lgkmcnt(1)
	v_mfma_f32_32x32x16_bf16 v[32:47], v[190:193], v[196:199], v[32:47]
	ds_read_b128 v[210:213], v230 offset:50688
	v_exp_f32_e32 v246, v130
	v_exp_f32_e32 v247, v131
	s_waitcnt lgkmcnt(1)
	v_mfma_f32_32x32x16_bf16 v[16:31], v[156:159], v[196:199], v[16:31]
	ds_read_b128 v[128:131], v230 offset:36896
	v_exp_f32_e32 v248, v132
	v_exp_f32_e32 v249, v133
	s_waitcnt lgkmcnt(1)
	v_mfma_f32_32x32x16_bf16 v[0:15], v[210:213], v[196:199], v[0:15]
	ds_read_b128 v[156:159], v230 offset:41504
	v_exp_f32_e32 v196, v134
	v_exp_f32_e32 v197, v135
	s_waitcnt lgkmcnt(1)
	v_mfma_f32_32x32x16_bf16 v[48:63], v[128:131], v[152:155], v[48:63]
	ds_read_b128 v[132:135], v230 offset:46112
	v_cvt_pk_bf16_f32 v128, v244, v245
	v_cvt_pk_bf16_f32 v129, v246, v247
	v_cvt_pk_bf16_f32 v130, v248, v249
	v_cvt_pk_bf16_f32 v131, v196, v197
	s_waitcnt lgkmcnt(1)
	v_mfma_f32_32x32x16_bf16 v[32:47], v[156:159], v[152:155], v[32:47]
	ds_read_b128 v[190:193], v230 offset:50720
	v_exp_f32_e32 v198, v136
	v_exp_f32_e32 v199, v137
	s_waitcnt lgkmcnt(1)
	v_mfma_f32_32x32x16_bf16 v[16:31], v[132:135], v[152:155], v[16:31]
	ds_read_b128 v[156:159], v230 offset:36928
	v_exp_f32_e32 v210, v138
	v_exp_f32_e32 v211, v139
	s_waitcnt lgkmcnt(1)
	v_mfma_f32_32x32x16_bf16 v[0:15], v[190:193], v[152:155], v[0:15]
	ds_read_b128 v[132:135], v230 offset:41536
	v_exp_f32_e32 v190, v140
	v_exp_f32_e32 v191, v141
	s_waitcnt lgkmcnt(1)
	v_mfma_f32_32x32x16_bf16 v[48:63], v[156:159], v[128:131], v[48:63]
	ds_read_b128 v[136:139], v230 offset:46144
	v_exp_f32_e32 v156, v142
	v_exp_f32_e32 v157, v143
	v_cvt_pk_bf16_f32 v140, v198, v199
	v_cvt_pk_bf16_f32 v141, v210, v211
	v_cvt_pk_bf16_f32 v142, v190, v191
	v_cvt_pk_bf16_f32 v143, v156, v157
	s_waitcnt lgkmcnt(1)
	v_mfma_f32_32x32x16_bf16 v[32:47], v[132:135], v[128:131], v[32:47]
	ds_read_b128 v[152:155], v230 offset:50752
	v_add_f32_e64 v158, v190, v236
	v_add_f32_e64 v159, v191, v237
	v_add_f32_e64 v156, v156, v242
	v_add_f32_e64 v157, v157, v243
	v_pk_add_f32 v[190:191], v[210:211], v[214:215]
	v_pk_add_f32 v[150:151], v[198:199], v[150:151]
	v_pk_add_f32 v[146:147], v[248:249], v[146:147]
	v_pk_add_f32 v[192:193], v[244:245], v[216:217]
	v_pk_add_f32 v[148:149], v[196:197], v[148:149]
	v_pk_add_f32 v[144:145], v[246:247], v[144:145]
	s_waitcnt lgkmcnt(1)
	v_mfma_f32_32x32x16_bf16 v[16:31], v[136:139], v[128:131], v[16:31]
	v_add_f32_e64 v136, v144, v148
	v_add_f32_e64 v137, v145, v149
	v_add_f32_e64 v138, v192, v146
	v_add_f32_e64 v139, v193, v147
	v_add_f32_e64 v136, v190, v136
	v_add_f32_e64 v137, v191, v137
	v_pk_add_f32 v[138:139], v[150:151], v[138:139]
	v_pk_add_f32 v[136:137], v[156:157], v[136:137]
	v_pk_add_f32 v[138:139], v[158:159], v[138:139]
	ds_read_b128 v[132:135], v230 offset:36960
	v_pk_mov_b32 v[144:145], v[138:139], v[136:137] op_sel:[1,0]
	v_mov_b32_e32 v139, v137
	v_pk_add_f32 v[136:137], v[144:145], v[138:139]
	s_nop 0
	v_add_f32_e32 v136, v136, v137
	v_add_f32_e32 v216, v234, v136
	s_waitcnt lgkmcnt(1)
	v_mfma_f32_32x32x16_bf16 v[0:15], v[152:155], v[128:131], v[0:15]
	ds_read_b128 v[136:139], v230 offset:41568
	v_max3_f32 v128, v112, v113, v80
	v_max3_f32 v144, v114, v115, v81
	v_max3_f32 v145, v128, v82, v83
	s_waitcnt lgkmcnt(1)
	v_mfma_f32_32x32x16_bf16 v[48:63], v[132:135], v[140:143], v[48:63]
	ds_read_b128 v[128:131], v230 offset:46176
	v_max3_f32 v132, v145, v116, v117
	v_max3_f32 v133, v144, v118, v119
	v_max3_f32 v144, v132, v84, v85
	v_max3_f32 v145, v133, v86, v87
	s_waitcnt lgkmcnt(1)
	v_mfma_f32_32x32x16_bf16 v[32:47], v[136:139], v[140:143], v[32:47]
	ds_read_b128 v[132:135], v230 offset:50784
	v_max3_f32 v136, v144, v120, v121
	v_max3_f32 v137, v145, v122, v123
	v_max3_f32 v136, v136, v88, v89
	v_max3_f32 v137, v137, v90, v91
	s_waitcnt lgkmcnt(1)
	v_mfma_f32_32x32x16_bf16 v[16:31], v[128:131], v[140:143], v[16:31]
	v_max3_f32 v128, v136, v124, v125
	v_max3_f32 v129, v137, v126, v127
	v_max3_f32 v128, v128, v92, v93
	v_max3_f32 v129, v129, v94, v95
	s_waitcnt lgkmcnt(0)
	v_mfma_f32_32x32x16_bf16 v[0:15], v[132:135], v[140:143], v[0:15]
	v_max_f32_e32 v128, v128, v129
	v_mov_b32_e32 v129, v128
	s_nop 1
	v_permlane32_swap_b32_e32 v128, v129
	v_max_f32_e32 v128, v128, v129
	s_nop 0
	v_cmp_lt_f32_e32 vcc, s3, v128
	s_cbranch_vccz .LBB0_413
; __device__ __forceinline__ float fast_exp2(float x) { return __builtin_amdgcn_exp2f(x); }
; template <int DV, int PAR, bool KW = true, bool KL = true, bool VL = true>
; __device__ __forceinline__ void attn_iter_full(AttnState<DV>& S, int t, LAS unsigned char* lds) {
;     ...
;     if (__any(mx > 8.0f)) {
;         const float dl = fmaxf(mx, 0.f), alpha = fast_exp2(-dl);
;         S.mrun += dl; S.lsum *= alpha;
; #pragma unroll
;         for (int i = 0; i < 16; ++i) { sn0[i] -= dl; sn1[i] -= dl; S.negm[i] = -S.mrun; }
; #pragma unroll
;         for (int d = 0; d < NDB; ++d)
; #pragma unroll
;             for (int i = 0; i < 16; ++i) S.o[d][i] *= alpha;
;     }
	v_max_f32_e32 v64, v128, v128
	v_max_f32_e32 v65, 0, v64
	v_exp_f32_e64 v66, -v65
	v_add_f32_e32 v233, v233, v65
	v_xor_b32_e32 v64, 0x80000000, v233
	v_sub_f32_e32 v127, v127, v65
	v_mul_f32_e32 v216, v216, v66
	v_sub_f32_e32 v126, v126, v65
	v_sub_f32_e32 v125, v125, v65
	v_sub_f32_e32 v124, v124, v65
	v_sub_f32_e32 v123, v123, v65
	v_sub_f32_e32 v122, v122, v65
	v_sub_f32_e32 v121, v121, v65
	v_sub_f32_e32 v120, v120, v65
	v_sub_f32_e32 v119, v119, v65
	v_sub_f32_e32 v118, v118, v65
	v_sub_f32_e32 v117, v117, v65
	v_sub_f32_e32 v116, v116, v65
	v_sub_f32_e32 v115, v115, v65
	v_sub_f32_e32 v114, v114, v65
	v_sub_f32_e32 v113, v113, v65
	v_sub_f32_e32 v112, v112, v65
	v_sub_f32_e32 v95, v95, v65
	v_sub_f32_e32 v94, v94, v65
	v_sub_f32_e32 v93, v93, v65
	v_sub_f32_e32 v92, v92, v65
	v_sub_f32_e32 v91, v91, v65
	v_sub_f32_e32 v90, v90, v65
	v_sub_f32_e32 v89, v89, v65
	v_sub_f32_e32 v88, v88, v65
	v_sub_f32_e32 v87, v87, v65
	v_sub_f32_e32 v86, v86, v65
	v_sub_f32_e32 v85, v85, v65
	v_sub_f32_e32 v84, v84, v65
	v_sub_f32_e32 v83, v83, v65
	v_sub_f32_e32 v82, v82, v65
	v_sub_f32_e32 v81, v81, v65
	v_sub_f32_e32 v80, v80, v65
	v_pk_mul_f32 v[62:63], v[62:63], v[66:67] op_sel_hi:[1,0]
	v_pk_mul_f32 v[60:61], v[60:61], v[66:67] op_sel_hi:[1,0]
	v_pk_mul_f32 v[58:59], v[58:59], v[66:67] op_sel_hi:[1,0]
	v_pk_mul_f32 v[56:57], v[56:57], v[66:67] op_sel_hi:[1,0]
	v_pk_mul_f32 v[54:55], v[54:55], v[66:67] op_sel_hi:[1,0]
	v_pk_mul_f32 v[52:53], v[52:53], v[66:67] op_sel_hi:[1,0]
	v_pk_mul_f32 v[50:51], v[50:51], v[66:67] op_sel_hi:[1,0]
	v_pk_mul_f32 v[48:49], v[48:49], v[66:67] op_sel_hi:[1,0]
	v_pk_mul_f32 v[46:47], v[46:47], v[66:67] op_sel_hi:[1,0]
	v_pk_mul_f32 v[44:45], v[44:45], v[66:67] op_sel_hi:[1,0]
	v_pk_mul_f32 v[42:43], v[42:43], v[66:67] op_sel_hi:[1,0]
	v_pk_mul_f32 v[40:41], v[40:41], v[66:67] op_sel_hi:[1,0]
	v_pk_mul_f32 v[38:39], v[38:39], v[66:67] op_sel_hi:[1,0]
	v_pk_mul_f32 v[36:37], v[36:37], v[66:67] op_sel_hi:[1,0]
	v_pk_mul_f32 v[34:35], v[34:35], v[66:67] op_sel_hi:[1,0]
	v_pk_mul_f32 v[32:33], v[32:33], v[66:67] op_sel_hi:[1,0]
	v_pk_mul_f32 v[30:31], v[30:31], v[66:67] op_sel_hi:[1,0]
	v_pk_mul_f32 v[28:29], v[28:29], v[66:67] op_sel_hi:[1,0]
	v_pk_mul_f32 v[26:27], v[26:27], v[66:67] op_sel_hi:[1,0]
	v_pk_mul_f32 v[24:25], v[24:25], v[66:67] op_sel_hi:[1,0]
	v_pk_mul_f32 v[22:23], v[22:23], v[66:67] op_sel_hi:[1,0]
	v_pk_mul_f32 v[20:21], v[20:21], v[66:67] op_sel_hi:[1,0]
	v_pk_mul_f32 v[18:19], v[18:19], v[66:67] op_sel_hi:[1,0]
	v_pk_mul_f32 v[16:17], v[16:17], v[66:67] op_sel_hi:[1,0]
	v_pk_mul_f32 v[14:15], v[14:15], v[66:67] op_sel_hi:[1,0]
	v_pk_mul_f32 v[12:13], v[12:13], v[66:67] op_sel_hi:[1,0]
	v_pk_mul_f32 v[10:11], v[10:11], v[66:67] op_sel_hi:[1,0]
	v_pk_mul_f32 v[8:9], v[8:9], v[66:67] op_sel_hi:[1,0]
	v_pk_mul_f32 v[6:7], v[6:7], v[66:67] op_sel_hi:[1,0]
	v_pk_mul_f32 v[4:5], v[4:5], v[66:67] op_sel_hi:[1,0]
	v_pk_mul_f32 v[2:3], v[2:3], v[66:67] op_sel_hi:[1,0]
	v_pk_mul_f32 v[0:1], v[0:1], v[66:67] op_sel_hi:[1,0]
	v_mov_b32_e32 v65, v64
	v_mov_b32_e32 v66, v64
	v_mov_b32_e32 v67, v64
	v_mov_b32_e32 v68, v64
	v_mov_b32_e32 v69, v64
	v_mov_b32_e32 v70, v64
	v_mov_b32_e32 v71, v64
	v_mov_b32_e32 v72, v64
	v_mov_b32_e32 v73, v64
	v_mov_b32_e32 v74, v64
	v_mov_b32_e32 v75, v64
	v_mov_b32_e32 v76, v64
	v_mov_b32_e32 v77, v64
	v_mov_b32_e32 v78, v64
	v_mov_b32_e32 v79, v64
	v_mov_b32_e32 v96, v64
	v_mov_b32_e32 v97, v64
	v_mov_b32_e32 v98, v64
	v_mov_b32_e32 v99, v64
	v_mov_b32_e32 v100, v64
	v_mov_b32_e32 v101, v64
	v_mov_b32_e32 v102, v64
	v_mov_b32_e32 v103, v64
	v_mov_b32_e32 v104, v64
	v_mov_b32_e32 v105, v64
	v_mov_b32_e32 v106, v64
	v_mov_b32_e32 v107, v64
	v_mov_b32_e32 v108, v64
	v_mov_b32_e32 v109, v64
	v_mov_b32_e32 v110, v64
	v_mov_b32_e32 v111, v64
	s_branch .LBB0_413

; __device__ __forceinline__ unsigned pk2(float lo, float hi) { f32x2_t v = {lo, hi}; bf16x2_t b = __builtin_convertvector(v, bf16x2_t); return __builtin_bit_cast(unsigned, b); }
; __device__ __forceinline__ float fast_exp2(float x) { return __builtin_amdgcn_exp2f(x); }
; #define MFMA32(a, b, c) __builtin_amdgcn_mfma_f32_32x32x16_bf16((a), (b), (c), 0, 0, 0)
; template <int DV, bool FULL>
; __device__ __forceinline__ void attn_iter(AttnState<DV>& S, int t, int nt, LAS unsigned char* lds) {
;     ...
;     f32x16 p0, p1;
; #pragma unroll
;     for (int i = 0; i < 16; ++i) { p0[i] = fast_exp2(S.sc0[i]); p1[i] = fast_exp2(S.sc1[i]); }
;     { const f32x16 s = p0 + p1; const f32x4 a = (f32x4){s[0], s[1], s[2], s[3]} + (f32x4){s[4], s[5], s[6], s[7]} + (f32x4){s[8], s[9], s[10], s[11]} + (f32x4){s[12], s[13], s[14], s[15]};
;       S.lsum += (a[0] + a[1]) + (a[2] + a[3]); }
; #pragma unroll
;     for (int blk = 0; blk < 2; ++blk)
; #pragma unroll
;         for (int a = 0; a < 2; ++a) {
;             u32x4 pw;
;             if (blk == 0) { pw.x = pk2(p0[8 * a], p0[8 * a + 1]); pw.y = pk2(p0[8 * a + 2], p0[8 * a + 3]); pw.z = pk2(p0[8 * a + 4], p0[8 * a + 5]); pw.w = pk2(p0[8 * a + 6], p0[8 * a + 7]); }
;             else { pw.x = pk2(p1[8 * a], p1[8 * a + 1]); pw.y = pk2(p1[8 * a + 2], p1[8 * a + 3]); pw.z = pk2(p1[8 * a + 4], p1[8 * a + 5]); pw.w = pk2(p1[8 * a + 6], p1[8 * a + 7]); }
;             const bf16x8 pp = __builtin_bit_cast(bf16x8, pw);
; #pragma unroll
;             for (int d = 0; d < NDB; ++d) { const bf16x8 vf = lds_rd16(BV + S.voff + d * 32 * 144 + (32 * blk + 16 * a) * 2); S.o[d] = MFMA32(vf, pp, S.o[d]); }
;         }
; __device__ __forceinline__ void diff_unit(const Params& p, int l, int b, int h, int qb, bool ctxq, LAS unsigned char* lds) {
;     ...
;     attn_pass<128>(Q1, K1, VT, nt, o1, l1, lds);
;     { const float i1 = 1.0f / l1;
; #pragma unroll
;       for (int d = 0; d < 4; ++d)
; #pragma unroll
;           for (int i = 0; i < 8; ++i) stash[(d * 8 + i) * 512] = pk2(o1[d][2 * i] * i1, o1[d][2 * i + 1] * i1); }
.LBB0_425:
	s_barrier
	ds_read_b128 v[82:85], v230 offset:36864
	ds_read_b128 v[90:93], v230 offset:36896
	v_exp_f32_e32 v112, v96
	v_exp_f32_e32 v113, v97
	v_exp_f32_e32 v114, v98
	v_exp_f32_e32 v115, v99
	v_exp_f32_e32 v116, v100
	v_exp_f32_e32 v117, v101
	v_exp_f32_e32 v118, v102
	v_exp_f32_e32 v119, v103
	v_cvt_pk_bf16_f32 v86, v112, v113
	v_cvt_pk_bf16_f32 v87, v114, v115
	v_cvt_pk_bf16_f32 v88, v116, v117
	v_cvt_pk_bf16_f32 v89, v118, v119
	v_exp_f32_e32 v120, v104
	v_exp_f32_e32 v121, v105
	s_waitcnt lgkmcnt(1)
	v_mfma_f32_32x32x16_bf16 v[48:63], v[82:85], v[86:89], v[48:63]
	ds_read_b128 v[82:85], v230 offset:41472
	ds_read_b128 v[94:97], v230 offset:41504
	v_exp_f32_e32 v106, v106
	v_exp_f32_e32 v107, v107
	v_exp_f32_e32 v108, v108
	v_exp_f32_e32 v109, v109
	v_lshl_add_u32 v232, v195, 2, 0
	v_add_u32_e32 v231, 0xd800, v232
	s_waitcnt lgkmcnt(1)
	v_mfma_f32_32x32x16_bf16 v[32:47], v[82:85], v[86:89], v[32:47]
	ds_read_b128 v[82:85], v230 offset:46080
	ds_read_b128 v[98:101], v230 offset:46112
	ds_read_b128 v[102:105], v230 offset:50720
	s_mov_b32 s2, 0x88000
	s_mov_b32 s64, s65
	s_mov_b32 s66, s65
	s_mov_b32 s67, s65
	s_mov_b32 s68, s65
	s_waitcnt lgkmcnt(2)
	v_mfma_f32_32x32x16_bf16 v[16:31], v[82:85], v[86:89], v[16:31]
	ds_read_b128 v[82:85], v230 offset:50688
	s_mov_b32 s69, s65
	s_mov_b32 s70, s65
	s_mov_b32 s71, s65
	s_mov_b32 s72, s65
	s_mov_b32 s73, s65
	s_mov_b32 s74, s65
	s_waitcnt lgkmcnt(0)
	v_mfma_f32_32x32x16_bf16 v[0:15], v[82:85], v[86:89], v[0:15]
	v_exp_f32_e32 v86, v110
	v_exp_f32_e32 v87, v111
	v_cvt_pk_bf16_f32 v82, v120, v121
	v_cvt_pk_bf16_f32 v83, v106, v107
	v_cvt_pk_bf16_f32 v84, v108, v109
	v_cvt_pk_bf16_f32 v85, v86, v87
	v_exp_f32_e32 v88, v64
	v_exp_f32_e32 v89, v65
	v_mfma_f32_32x32x16_bf16 v[32:47], v[94:97], v[82:85], v[32:47]
	v_exp_f32_e32 v94, v70
	v_exp_f32_e32 v95, v71
	v_exp_f32_e32 v96, v72
	v_exp_f32_e32 v97, v73
	v_exp_f32_e32 v110, v76
	v_exp_f32_e32 v111, v77
	v_cvt_pk_bf16_f32 v71, v94, v95
	v_mfma_f32_32x32x16_bf16 v[48:63], v[90:93], v[82:85], v[48:63]
	v_exp_f32_e32 v90, v66
	v_exp_f32_e32 v91, v67
	ds_read_b128 v[64:67], v230 offset:36928
	v_exp_f32_e32 v92, v68
	v_exp_f32_e32 v93, v69
	v_cvt_pk_bf16_f32 v68, v88, v89
	v_cvt_pk_bf16_f32 v69, v90, v91
	v_mfma_f32_32x32x16_bf16 v[16:31], v[98:101], v[82:85], v[16:31]
	v_exp_f32_e32 v98, v78
	v_exp_f32_e32 v99, v79
	v_exp_f32_e32 v100, v74
	v_exp_f32_e32 v101, v75
	ds_read_b128 v[72:75], v230 offset:41536
	ds_read_b128 v[76:79], v230 offset:36960
	v_cvt_pk_bf16_f32 v70, v92, v93
	v_pk_add_f32 v[94:95], v[94:95], v[118:119]
	v_mfma_f32_32x32x16_bf16 v[0:15], v[102:105], v[82:85], v[0:15]
	v_add_f32_e64 v90, v90, v114
	v_add_f32_e64 v91, v91, v115
	v_add_f32_e64 v102, v100, v106
	v_add_f32_e64 v103, v101, v107
	v_add_f32_e64 v92, v92, v116
	v_add_f32_e64 v93, v93, v117
	v_pk_add_f32 v[88:89], v[88:89], v[112:113]
	v_pk_add_f32 v[86:87], v[98:99], v[86:87]
	v_pk_add_f32 v[104:105], v[96:97], v[120:121]
	v_pk_add_f32 v[108:109], v[110:111], v[108:109]
	s_waitcnt lgkmcnt(1)
	v_mfma_f32_32x32x16_bf16 v[32:47], v[72:75], v[68:71], v[32:47]
	v_add_f32_e64 v72, v90, v94
	v_add_f32_e64 v73, v91, v95
	v_add_f32_e64 v74, v88, v92
	v_add_f32_e64 v75, v89, v93
	v_add_f32_e64 v72, v102, v72
	v_add_f32_e64 v73, v103, v73
	v_pk_add_f32 v[90:91], v[104:105], v[74:75]
	v_pk_add_f32 v[92:93], v[86:87], v[72:73]
	s_mov_b32 s75, s65
	s_mov_b32 s76, s65
	v_mfma_f32_32x32x16_bf16 v[48:63], v[64:67], v[68:71], v[48:63]
	ds_read_b128 v[64:67], v230 offset:46144
	ds_read_b128 v[82:85], v230 offset:41568
	ds_read_b128 v[72:75], v230 offset:50752
	ds_read_b128 v[86:89], v230 offset:46176
	s_mov_b32 s77, s65
	s_mov_b32 s78, s65
	s_mov_b32 s79, s65
	v_mov_b32_e32 v216, 0
	s_waitcnt lgkmcnt(3)
	v_mfma_f32_32x32x16_bf16 v[16:31], v[64:67], v[68:71], v[16:31]
	v_add_f32_e64 v64, v108, v90
	v_add_f32_e64 v65, v109, v91
	v_pk_mov_b32 v[66:67], v[64:65], v[92:93] op_sel:[1,0]
	v_mov_b32_e32 v65, v93
	v_pk_add_f32 v[64:65], v[66:67], v[64:65]
	s_nop 0
	v_add_f32_e32 v64, v64, v65
	s_waitcnt lgkmcnt(1)
	v_mfma_f32_32x32x16_bf16 v[0:15], v[72:75], v[68:71], v[0:15]
	v_and_b32_e32 v73, 64, v224
	v_xor_b32_e32 v72, 32, v224
	v_add_u32_e32 v73, 64, v73
	v_cmp_lt_i32_e32 vcc, v72, v73
	v_add_f32_e32 v80, v80, v64
	ds_read_b128 v[64:67], v230 offset:50784
	v_cndmask_b32_e32 v72, v224, v72, vcc
	v_lshlrev_b32_e32 v230, 2, v72
	ds_bpermute_b32 v72, v230, v80
	v_cvt_pk_bf16_f32 v68, v96, v97
	v_cvt_pk_bf16_f32 v69, v100, v101
	v_cvt_pk_bf16_f32 v70, v110, v111
	v_cvt_pk_bf16_f32 v71, v98, v99
	s_waitcnt lgkmcnt(0)
	v_add_f32_e32 v72, v80, v72
	v_div_scale_f32 v73, s[16:17], v72, v72, 1.0
	v_rcp_f32_e32 v74, v73
	v_mfma_f32_32x32x16_bf16 v[48:63], v[76:79], v[68:71], v[48:63]
	s_barrier
; #define LAS __attribute__((address_space(3)))
; __device__ __forceinline__ unsigned pk2(float lo, float hi) { f32x2_t v = {lo, hi}; bf16x2_t b = __builtin_convertvector(v, bf16x2_t); return __builtin_bit_cast(unsigned, b); }
; template <int DV>
; __device__ __forceinline__ void attn_pass(const bf16_t* __restrict__ Qp, const bf16_t* __restrict__ Kp, const bf16_t* __restrict__ VTp, int nt,
;                                           f32x16 (&o)[DV / 32], float& lout, LAS unsigned char* lds) {
;     ...
;     { const bf16_t* qrow = Qp + (size_t)(wid * 32 + r32) * 64 + hi * 8;
; #pragma unroll
;       for (int c = 0; c < 4; ++c) S.qr[c] = *(const bf16x8*)(qrow + c * 16); }
;     const int lrow = tid >> 3, lseg = tid & 7;
;     S.kg = Kp + (size_t)lrow * 64 + lseg * 8;
;     S.vg = VTp + (size_t)lrow * TK + lseg * 8;
;     S.kl = lrow * 144 + lseg * 16; S.vl = lrow * 144 + lseg * 16;
;     const int kvr = (r32 & ~12) | (((r32 >> 2) & 1) << 3) | (((r32 >> 3) & 1) << 2);
;     S.koff = kvr * 144 + hi * 16; S.voff = r32 * 144 + hi * 16;
;     { const u32x4 k0 = *(const u32x4*)S.kg, k1 = *(const u32x4*)(S.kg + 4096), v0 = *(const u32x4*)S.vg;
;       u32x4 v0b; if (DV == 128) v0b = *(const u32x4*)(S.vg + (size_t)64 * TK);
;       *(LAS u32x4*)(lds + AT_K0 + S.kl) = k0; *(LAS u32x4*)(lds + AT_K0 + AT_KB + S.kl) = k1; *(LAS u32x4*)(lds + AT_V0 + S.vl) = v0; if (DV == 128) *(LAS u32x4*)(lds + AT_V0 + S.vl + 64 * 144) = v0b; }
;     if (nt > 2) S.kreg = *(const u32x4*)(S.kg + (size_t)2 * 4096);
;     S.vreg0 = *(const u32x4*)(S.vg + 64); if (DV == 128) S.vreg1 = *(const u32x4*)(S.vg + (size_t)64 * TK + 64);
;     __syncthreads();
; __device__ __forceinline__ void diff_unit(const Params& p, int l, int b, int h, int qb, bool ctxq, LAS unsigned char* lds) {
;     ...
;     { const float i1 = 1.0f / l1;
; #pragma unroll
;       for (int d = 0; d < 4; ++d)
; #pragma unroll
;           for (int i = 0; i < 8; ++i) stash[(d * 8 + i) * 512] = pk2(o1[d][2 * i] * i1, o1[d][2 * i + 1] * i1); }
	v_fma_f32 v75, -v73, v74, 1.0
	v_fmac_f32_e32 v74, v75, v74
	v_div_scale_f32 v75, vcc, 1.0, v72, 1.0
	v_mul_f32_e32 v76, v75, v74
	v_fma_f32 v77, -v73, v76, v75
	v_fmac_f32_e32 v76, v77, v74
	v_fma_f32 v73, -v73, v76, v75
	v_mfma_f32_32x32x16_bf16 v[0:15], v[64:67], v[68:71], v[0:15]
	v_div_fmas_f32 v64, v73, v74, v76
	v_div_fixup_f32 v64, v64, v72, 1.0
	s_nop 0
	v_mul_f32_e64 v48, v48, v64
	v_mul_f32_e64 v49, v49, v64
	v_cvt_pk_bf16_f32 v65, v48, v49
	v_pk_mul_f32 v[48:49], v[50:51], v[64:65] op_sel_hi:[1,0]
	s_nop 4
	v_pk_mul_f32 v[0:1], v[0:1], v[64:65] op_sel_hi:[1,0]
	v_cvt_pk_bf16_f32 v48, v48, v49
	v_mfma_f32_32x32x16_bf16 v[32:47], v[82:85], v[68:71], v[32:47]
	ds_write2st64_b32 v232, v65, v48 offset0:216 offset1:224
	v_mul_f32_e64 v48, v52, v64
	v_mul_f32_e64 v49, v53, v64
	v_cvt_pk_bf16_f32 v0, v0, v1
	v_cvt_pk_bf16_f32 v50, v48, v49
	v_pk_mul_f32 v[48:49], v[54:55], v[64:65] op_sel_hi:[1,0]
	v_mov_b32_e32 v54, v218
	v_cvt_pk_bf16_f32 v48, v48, v49
	ds_write2st64_b32 v232, v50, v48 offset0:232 offset1:240
	v_pk_mul_f32 v[48:49], v[56:57], v[64:65] op_sel_hi:[1,0]
	s_nop 1
	v_pk_mul_f32 v[32:33], v[32:33], v[64:65] op_sel_hi:[1,0]
	v_cvt_pk_bf16_f32 v48, v48, v49
	ds_write_b32 v232, v48 offset:63488
	v_pk_mul_f32 v[48:49], v[58:59], v[64:65] op_sel_hi:[1,0]
	v_cvt_pk_bf16_f32 v32, v32, v33
	v_cvt_pk_bf16_f32 v50, v48, v49
	v_pk_mul_f32 v[48:49], v[60:61], v[64:65] op_sel_hi:[1,0]
	v_mfma_f32_32x32x16_bf16 v[16:31], v[86:89], v[68:71], v[16:31]
	v_cvt_pk_bf16_f32 v48, v48, v49
	ds_write2st64_b32 v231, v50, v48 offset0:40 offset1:48
	v_mul_f32_e64 v48, v62, v64
	v_mul_f32_e64 v49, v63, v64
	v_mov_b32_e32 v57, v161
	v_cvt_pk_bf16_f32 v48, v48, v49
	ds_write2st64_b32 v231, v48, v32 offset0:56 offset1:64
	v_pk_mul_f32 v[32:33], v[34:35], v[64:65] op_sel_hi:[1,0]
	s_nop 3
	v_pk_mul_f32 v[16:17], v[16:17], v[64:65] op_sel_hi:[1,0]
	v_cvt_pk_bf16_f32 v34, v32, v33
	v_pk_mul_f32 v[32:33], v[36:37], v[64:65] op_sel_hi:[1,0]
	v_cvt_pk_bf16_f32 v16, v16, v17
	v_cvt_pk_bf16_f32 v32, v32, v33
	ds_write2st64_b32 v231, v34, v32 offset0:72 offset1:80
	v_pk_mul_f32 v[32:33], v[38:39], v[64:65] op_sel_hi:[1,0]
	s_nop 0
	v_cvt_pk_bf16_f32 v34, v32, v33
	v_pk_mul_f32 v[32:33], v[40:41], v[64:65] op_sel_hi:[1,0]
	s_nop 0
	v_cvt_pk_bf16_f32 v32, v32, v33
	ds_write2st64_b32 v231, v34, v32 offset0:88 offset1:96
	v_pk_mul_f32 v[32:33], v[42:43], v[64:65] op_sel_hi:[1,0]
	s_nop 0
	v_cvt_pk_bf16_f32 v34, v32, v33
	v_pk_mul_f32 v[32:33], v[44:45], v[64:65] op_sel_hi:[1,0]
	s_nop 0
	v_cvt_pk_bf16_f32 v32, v32, v33
	ds_write2st64_b32 v231, v34, v32 offset0:104 offset1:112
	v_pk_mul_f32 v[32:33], v[46:47], v[64:65] op_sel_hi:[1,0]
	s_nop 0
	v_cvt_pk_bf16_f32 v32, v32, v33
	ds_write2st64_b32 v231, v32, v16 offset0:120 offset1:128
	v_pk_mul_f32 v[16:17], v[18:19], v[64:65] op_sel_hi:[1,0]
	s_nop 0
	v_cvt_pk_bf16_f32 v18, v16, v17
	v_pk_mul_f32 v[16:17], v[20:21], v[64:65] op_sel_hi:[1,0]
	s_nop 0
	v_cvt_pk_bf16_f32 v16, v16, v17
	ds_write2st64_b32 v231, v18, v16 offset0:136 offset1:144
	v_pk_mul_f32 v[16:17], v[22:23], v[64:65] op_sel_hi:[1,0]
	s_nop 0
	v_cvt_pk_bf16_f32 v18, v16, v17
	v_pk_mul_f32 v[16:17], v[24:25], v[64:65] op_sel_hi:[1,0]
	s_nop 0
	v_cvt_pk_bf16_f32 v16, v16, v17
	ds_write2st64_b32 v231, v18, v16 offset0:152 offset1:160
	v_pk_mul_f32 v[16:17], v[26:27], v[64:65] op_sel_hi:[1,0]
	s_nop 0
	v_cvt_pk_bf16_f32 v18, v16, v17
	v_pk_mul_f32 v[16:17], v[28:29], v[64:65] op_sel_hi:[1,0]
	s_nop 0
	v_cvt_pk_bf16_f32 v16, v16, v17
	ds_write2st64_b32 v231, v18, v16 offset0:168 offset1:176
	v_pk_mul_f32 v[16:17], v[30:31], v[64:65] op_sel_hi:[1,0]
	s_nop 0
	v_cvt_pk_bf16_f32 v16, v16, v17
	ds_write2st64_b32 v231, v16, v0 offset0:184 offset1:192
	v_pk_mul_f32 v[0:1], v[2:3], v[64:65] op_sel_hi:[1,0]
	s_nop 0
	v_cvt_pk_bf16_f32 v2, v0, v1
	v_pk_mul_f32 v[0:1], v[4:5], v[64:65] op_sel_hi:[1,0]
	s_nop 0
	v_cvt_pk_bf16_f32 v0, v0, v1
	ds_write2st64_b32 v231, v2, v0 offset0:200 offset1:208
	v_pk_mul_f32 v[0:1], v[6:7], v[64:65] op_sel_hi:[1,0]
	s_nop 0
	v_cvt_pk_bf16_f32 v2, v0, v1
	v_pk_mul_f32 v[0:1], v[8:9], v[64:65] op_sel_hi:[1,0]
	s_nop 0
	v_cvt_pk_bf16_f32 v0, v0, v1
	ds_write2st64_b32 v231, v2, v0 offset0:216 offset1:224
	v_pk_mul_f32 v[0:1], v[10:11], v[64:65] op_sel_hi:[1,0]
	s_nop 0
	v_cvt_pk_bf16_f32 v2, v0, v1
	v_pk_mul_f32 v[0:1], v[12:13], v[64:65] op_sel_hi:[1,0]
	s_nop 0
	v_cvt_pk_bf16_f32 v0, v0, v1
	ds_write2st64_b32 v231, v2, v0 offset0:232 offset1:240
	v_pk_mul_f32 v[0:1], v[14:15], v[64:65] op_sel_hi:[1,0]
	s_nop 0
	v_cvt_pk_bf16_f32 v0, v0, v1
	ds_write_b32 v231, v0 offset:63488
	s_nop 0
	v_ashrrev_i32_e32 v48, 3, v54
	v_ashrrev_i32_e32 v49, 31, v48
	v_lshlrev_b64 v[50:51], 7, v[48:49]
	v_lshlrev_b32_e32 v2, 4, v54
	v_lshl_add_u64 v[0:1], s[6:7], 0, v[50:51]
	v_and_b32_e32 v160, 0x70, v2
	v_lshl_add_u64 v[52:53], v[0:1], 0, v[160:161]
	v_mov_b64_e32 v[0:1], s[8:9]
	s_movk_i32 s8, 0x2200
	v_mad_i64_i32 v[0:1], s[6:7], v48, s8, v[0:1]
	v_lshl_add_u64 v[202:203], v[0:1], 0, v[160:161]
	v_add_co_u32_e32 v0, vcc, s2, v52
	s_mov_b32 s6, 0x8a000
	s_nop 0
	v_addc_co_u32_e32 v1, vcc, 0, v53, vcc
	v_add_co_u32_e32 v4, vcc, s6, v52
	v_ashrrev_i32_e32 v18, 1, v54
	s_nop 0
	v_addc_co_u32_e32 v5, vcc, 0, v53, vcc
	global_load_dwordx4 v[0:3], v[0:1], off
	s_nop 0
	global_load_dwordx4 v[4:7], v[4:5], off
	s_nop 0
	global_load_dwordx4 v[8:11], v[202:203], off
	v_add_co_u32_e32 v16, vcc, s2, v202
	s_movk_i32 s2, 0xffe0
	v_bfi_b32 v18, s2, v18, v54
	v_ashrrev_i32_e32 v19, 31, v18
	v_addc_co_u32_e32 v17, vcc, 0, v203, vcc
	v_lshlrev_b64 v[18:19], 7, v[18:19]
	v_lshrrev_b32_e32 v22, 1, v54
	global_load_dwordx4 v[12:15], v[16:17], off
	v_lshl_add_u64 v[18:19], s[4:5], 0, v[18:19]
	v_and_b32_e32 v56, 16, v22
	v_lshl_add_u64 v[18:19], v[18:19], 0, v[56:57]
	s_mov_b32 s2, 0x80000
	v_add_co_u32_e32 v20, vcc, s2, v18
	s_mov_b64 s[4:5], 0x80000
	s_nop 0
	v_addc_co_u32_e32 v21, vcc, 0, v19, vcc
	global_load_dwordx4 v[174:177], v[20:21], off
	v_lshl_add_u64 v[18:19], v[18:19], 0, s[4:5]
	global_load_dwordx4 v[170:173], v[18:19], off offset:32
	global_load_dwordx4 v[166:169], v[18:19], off offset:64
	global_load_dwordx4 v[162:165], v[18:19], off offset:96
	v_mad_u64_u32 v[18:19], s[4:5], v48, s92, v[160:161]
	v_add_u32_e32 v235, 0, v18
	s_mov_b32 s2, 0x8c000
	s_waitcnt vmcnt(7)
	ds_write_b128 v235, v[0:3]
	s_waitcnt vmcnt(6)
	ds_write_b128 v235, v[4:7] offset:9216
	v_add_co_u32_e32 v0, vcc, s2, v52
	global_load_dwordx4 v[178:181], v[202:203], off offset:128
	s_nop 0
	v_addc_co_u32_e32 v1, vcc, 0, v53, vcc
	global_load_dwordx4 v[182:185], v[16:17], off offset:128
	global_load_dwordx4 v[186:189], v[0:1], off
	v_lshlrev_b32_e32 v20, 1, v54
	v_and_b32_e32 v19, 19, v54
	v_and_b32_e32 v20, 8, v20
	v_and_b32_e32 v21, 4, v22
	v_or3_b32 v19, v19, v20, v21
	v_mad_u32_u24 v19, v19, s92, v56
	v_add_u32_e32 v234, 0, v19
	s_waitcnt vmcnt(8)
	ds_write_b128 v235, v[8:11] offset:18432
	s_waitcnt vmcnt(7)
	ds_write_b128 v235, v[12:15] offset:27648
	s_waitcnt lgkmcnt(0)
	s_barrier
; #define MFMA32(a, b, c) __builtin_amdgcn_mfma_f32_32x32x16_bf16((a), (b), (c), 0, 0, 0)
; template <int DV>
; __device__ __forceinline__ void attn_pass(const bf16_t* __restrict__ Qp, const bf16_t* __restrict__ Kp, const bf16_t* __restrict__ VTp, int nt,
;                                           f32x16 (&o)[DV / 32], float& lout, LAS unsigned char* lds) {
;     ...
;     for (int d = 0; d < NDB; ++d)
; #pragma unroll
;         for (int i = 0; i < 16; ++i) S.o[d][i] = 0.f;
;     S.lsum = 0.f;
;     {
;         f32x16 s0, s1;
; #pragma unroll
;         for (int i = 0; i < 16; ++i) { s0[i] = 0.f; s1[i] = 0.f; }
; #pragma unroll
;         for (int c = 0; c < 4; ++c) { const bf16x8 kf0 = lds_rd16(lds + AT_K0 + S.koff + c * 32), kf1 = lds_rd16(lds + AT_K0 + S.koff + 32 * 144 + c * 32);
;             s0 = MFMA32(kf0, S.qr[c], s0); s1 = MFMA32(kf1, S.qr[c], s1); }
;         const float mx = rowmax32(s0, s1);
;         S.mrun = mx;
; #pragma unroll
;         for (int i = 0; i < 16; ++i) { S.sc0[i] = s0[i] - mx; S.sc1[i] = s1[i] - mx; S.negm[i] = -mx; }
;     }
;     __syncthreads();
;     int t = 0;
;     for (; t + 4 < nt; t += 2) { attn_iter_full<DV, 0>(S, t, lds); attn_iter_full<DV, 1>(S, t + 1, lds); }
	ds_read_b128 v[0:3], v234
	ds_read_b128 v[4:7], v234 offset:32
	s_waitcnt vmcnt(6) lgkmcnt(1)
	v_mfma_f32_32x32x16_bf16 v[32:47], v[0:3], v[174:177], 0
	ds_read_b128 v[0:3], v234 offset:4608
	ds_read_b128 v[8:11], v234 offset:4640
	s_mov_b64 s[4:5], 0x88000
	v_lshl_add_u64 v[204:205], v[52:53], 0, s[4:5]
	s_add_u32 s4, s62, s12
	s_addc_u32 s5, s63, s1
	v_lshl_add_u64 v[206:207], s[4:5], 0, v[50:51]
	s_add_u32 s4, s62, s14
	s_waitcnt vmcnt(5) lgkmcnt(2)
	v_mfma_f32_32x32x16_bf16 v[32:47], v[4:7], v[170:173], v[32:47]
	s_addc_u32 s5, s63, s13
	s_mov_b32 s1, -2
	s_waitcnt lgkmcnt(1)
	v_mfma_f32_32x32x16_bf16 v[16:31], v[0:3], v[174:177], 0
	ds_read_b128 v[0:3], v234 offset:64
	ds_read_b128 v[4:7], v234 offset:96
	s_waitcnt vmcnt(4) lgkmcnt(1)
	v_mfma_f32_32x32x16_bf16 v[32:47], v[0:3], v[166:169], v[32:47]
	ds_read_b128 v[0:3], v234 offset:4672
	v_mfma_f32_32x32x16_bf16 v[16:31], v[8:11], v[170:173], v[16:31]
	v_and_b32_e32 v8, 31, v54
	ds_read_b128 v[52:55], v234 offset:4704
	v_mul_u32_u24_e32 v49, 0x90, v8
	v_add3_u32 v233, v56, v49, 0
	s_waitcnt lgkmcnt(0)
	s_barrier
	v_mfma_f32_32x32x16_bf16 v[16:31], v[0:3], v[166:169], v[16:31]
	s_waitcnt vmcnt(3)
	v_mfma_f32_32x32x16_bf16 v[32:47], v[4:7], v[162:165], v[32:47]
	v_mov_b64_e32 v[0:1], s[64:65]
	v_mov_b64_e32 v[14:15], s[78:79]
	v_mov_b64_e32 v[2:3], s[66:67]
	v_mov_b64_e32 v[4:5], s[68:69]
	v_mov_b64_e32 v[6:7], s[70:71]
	v_mov_b64_e32 v[8:9], s[72:73]
	v_mov_b64_e32 v[10:11], s[74:75]
	v_mfma_f32_32x32x16_bf16 v[16:31], v[52:55], v[162:165], v[16:31]
	v_max3_f32 v52, v32, v33, v16
	v_max3_f32 v53, v34, v35, v17
	v_mov_b64_e32 v[12:13], s[76:77]
	v_max3_f32 v52, v52, v18, v19
	v_max3_f32 v53, v53, v38, v39
	v_readlane_b32 s70, v255, 12
	v_max3_f32 v52, v52, v36, v37
	v_max3_f32 v53, v53, v22, v23
	v_readlane_b32 s71, v255, 13
	v_max3_f32 v52, v52, v20, v21
	v_max3_f32 v53, v53, v42, v43
	s_movk_i32 s74, 0x1100
	v_max3_f32 v52, v52, v40, v41
	v_max3_f32 v53, v53, v26, v27
	s_mov_b64 s[68:69], 0x2000
	v_max3_f32 v52, v52, v24, v25
	v_max3_f32 v53, v53, v46, v47
	s_mov_b64 s[72:73], 0x1000
	v_max3_f32 v52, v52, v44, v45
	v_max3_f32 v53, v53, v30, v31
	s_nop 0
	v_max3_f32 v52, v52, v28, v29
	s_nop 0
	v_max_f32_e32 v52, v52, v53
	s_nop 0
	v_mov_b32_e32 v53, v52
	s_nop 1
	v_permlane32_swap_b32_e32 v52, v53
	v_max_f32_e32 v236, v52, v53
	s_nop 0
	v_sub_f32_e32 v81, v17, v236
	v_sub_f32_e32 v80, v16, v236
	v_mov_b64_e32 v[16:17], s[4:5]
	v_xor_b32_e32 v96, 0x80000000, v236
	v_sub_f32_e32 v127, v47, v236
	v_sub_f32_e32 v126, v46, v236
	v_sub_f32_e32 v125, v45, v236
	v_sub_f32_e32 v124, v44, v236
	v_sub_f32_e32 v123, v43, v236
	v_sub_f32_e32 v122, v42, v236
	v_sub_f32_e32 v121, v41, v236
	v_sub_f32_e32 v120, v40, v236
	v_sub_f32_e32 v119, v39, v236
	v_sub_f32_e32 v118, v38, v236
	v_sub_f32_e32 v117, v37, v236
	v_sub_f32_e32 v116, v36, v236
	v_sub_f32_e32 v115, v35, v236
	v_sub_f32_e32 v114, v34, v236
	v_sub_f32_e32 v113, v33, v236
	v_sub_f32_e32 v112, v32, v236
	v_sub_f32_e32 v95, v31, v236
	v_sub_f32_e32 v94, v30, v236
	v_sub_f32_e32 v93, v29, v236
	v_sub_f32_e32 v92, v28, v236
	v_sub_f32_e32 v91, v27, v236
	v_sub_f32_e32 v90, v26, v236
	v_sub_f32_e32 v89, v25, v236
	v_sub_f32_e32 v88, v24, v236
	v_sub_f32_e32 v87, v23, v236
	v_sub_f32_e32 v86, v22, v236
	v_sub_f32_e32 v85, v21, v236
	v_sub_f32_e32 v84, v20, v236
	v_sub_f32_e32 v83, v19, v236
	v_sub_f32_e32 v82, v18, v236
	v_mad_i64_i32 v[208:209], s[4:5], v48, s8, v[16:17]
	v_mov_b64_e32 v[62:63], v[14:15]
	v_mov_b64_e32 v[46:47], v[14:15]
	v_mov_b64_e32 v[30:31], v[14:15]
	v_mov_b64_e32 v[60:61], v[12:13]
	v_mov_b64_e32 v[58:59], v[10:11]
	v_mov_b64_e32 v[56:57], v[8:9]
	v_mov_b64_e32 v[54:55], v[6:7]
	v_mov_b64_e32 v[52:53], v[4:5]
	v_mov_b64_e32 v[50:51], v[2:3]
	v_mov_b64_e32 v[48:49], v[0:1]
	v_mov_b64_e32 v[44:45], v[12:13]
	v_mov_b64_e32 v[42:43], v[10:11]
	v_mov_b64_e32 v[40:41], v[8:9]
	v_mov_b64_e32 v[38:39], v[6:7]
	v_mov_b64_e32 v[36:37], v[4:5]
	v_mov_b64_e32 v[34:35], v[2:3]
	v_mov_b64_e32 v[32:33], v[0:1]
	v_mov_b64_e32 v[28:29], v[12:13]
	v_mov_b64_e32 v[26:27], v[10:11]
	v_mov_b64_e32 v[24:25], v[8:9]
	v_mov_b64_e32 v[22:23], v[6:7]
	v_mov_b64_e32 v[20:21], v[4:5]
	v_mov_b64_e32 v[18:19], v[2:3]
	v_mov_b64_e32 v[16:17], v[0:1]
	v_mov_b32_e32 v97, v96
	v_mov_b32_e32 v98, v96
	v_mov_b32_e32 v99, v96
	v_mov_b32_e32 v100, v96
	v_mov_b32_e32 v101, v96
	v_mov_b32_e32 v102, v96
	v_mov_b32_e32 v103, v96
	v_mov_b32_e32 v104, v96
	v_mov_b32_e32 v105, v96
	v_mov_b32_e32 v106, v96
	v_mov_b32_e32 v107, v96
	v_mov_b32_e32 v108, v96
	v_mov_b32_e32 v109, v96
	v_mov_b32_e32 v110, v96
	v_mov_b32_e32 v111, v96
	s_mov_b32 s4, 0x10e8e000
	s_mov_b32 s5, 0
	v_lshl_add_u64 v[206:207], v[206:207], 0, s[4:5]
	v_lshl_add_u64 v[206:207], v[206:207], 0, v[160:161]
	s_mov_b32 s4, 0x13000000
	v_lshl_add_u64 v[208:209], v[208:209], 0, s[4:5]
	v_lshl_add_u64 v[208:209], v[208:209], 0, v[160:161]
	s_mov_b32 s4, 0x88000
	s_mov_b32 s100, 0x2000
	s_mov_b32 s101, 0
	s_branch .LBB0_427

; template <int DV, int PAR, bool KW = true, bool KL = true, bool VL = true>
; __device__ __forceinline__ void attn_iter_full(AttnState<DV>& S, int t, LAS unsigned char* lds) {
;     constexpr int NDB = DV / 32, NS = 8 + 4 * NDB, NU = 27;
;     const LAS unsigned char* BK = lds + AT_K0 + (PAR ^ 1) * AT_KB + S.koff;
;     const LAS unsigned char* BV = lds + AT_V0 + PAR * AT_VB + S.voff;
;     f32x16& C0 = PAR ? S.sd0 : S.sc0; f32x16& C1 = PAR ? S.sd1 : S.sc1; f32x16& sn0 = PAR ? S.sc0 : S.sd0; f32x16& sn1 = PAR ? S.sc1 : S.sd1;
;     sn0 = S.negm; sn1 = S.negm;
;     u32x4 pw[4]; float mxa = 0.f, mxb = 0.f, mx = 0.f; f32x16 ssum;
;     constexpr int PD = (DV == 64) ? 3 : 2; bf16x8 fr[PD + 1];
;     ...
; #pragma unroll
;     for (int i = 0; i < PD; ++i) fr[i] = AT_FRAG(i);
;     __builtin_amdgcn_sched_barrier(0);
; #pragma unroll
;     for (int i = 0; i < NS; ++i) {
;         if (i + PD < NS) fr[(i + PD) % (PD + 1)] = AT_FRAG(i + PD);
;         if (i == 3) {
;             if (KW) *(LAS u32x4*)(lds + AT_K0 + PAR * AT_KB + S.kl) = S.kreg;
;             LAS unsigned char* W = lds + AT_V0 + (PAR ^ 1) * AT_VB + S.vl; *(LAS u32x4*)W = S.vreg0; if (DV == 128) *(LAS u32x4*)(W + 64 * 144) = S.vreg1; }
;         if (i == 5) { if (KL) S.kreg = *(const u32x4*)(S.kg + (size_t)(t + 3) * 4096);
;             if (VL) { S.vreg0 = *(const u32x4*)(S.vg + (t + 2) * 64); if (DV == 128) S.vreg1 = *(const u32x4*)(S.vg + (size_t)64 * TK + (t + 2) * 64); } }
;         if (i < 8) { if (i & 1) sn1 = MFMA32(fr[i % (PD + 1)], S.qr[i >> 1], sn1); else sn0 = MFMA32(fr[i % (PD + 1)], S.qr[i >> 1], sn0); }
;         else { const int j = i - 8; S.o[j % NDB] = MFMA32(fr[i % (PD + 1)], __builtin_bit_cast(bf16x8, pw[j / NDB]), S.o[j % NDB]); }
; #pragma unroll
;         for (int u = 0; u < NU; ++u) {
;             if (u * NS / NU != i) continue;
;             if (u < 20) {
;                 const int q = u / 5, r = u % 5;
;                 if (r < 4) { const int e = 8 * q + 2 * r;
;                     if (e < 16) { C0[e] = fast_exp2(C0[e]); C0[e + 1] = fast_exp2(C0[e + 1]); }
;                     else { C1[e - 16] = fast_exp2(C1[e - 16]); C1[e - 15] = fast_exp2(C1[e - 15]); } }
;                 else { if (q < 2) { const int b0 = 8 * q; pw[q].x = pk2(C0[b0], C0[b0 + 1]); pw[q].y = pk2(C0[b0 + 2], C0[b0 + 3]); pw[q].z = pk2(C0[b0 + 4], C0[b0 + 5]); pw[q].w = pk2(C0[b0 + 6], C0[b0 + 7]); }
.LBB0_427:
	ds_read_b128 v[64:67], v234 offset:9216
	ds_read_b128 v[68:71], v234 offset:13824
	s_waitcnt lgkmcnt(1)
	v_mfma_f32_32x32x16_bf16 v[144:159], v[64:67], v[174:177], v[96:111]
	ds_read_b128 v[72:75], v234 offset:9248
	v_exp_f32_e32 v64, v114
	v_exp_f32_e32 v66, v112
	v_exp_f32_e32 v67, v113
	v_exp_f32_e32 v65, v115
	s_waitcnt lgkmcnt(1)
	v_mfma_f32_32x32x16_bf16 v[128:143], v[68:71], v[174:177], v[96:111]
	ds_read_b128 v[76:79], v234 offset:13856
	v_exp_f32_e32 v68, v116
	v_exp_f32_e32 v69, v117
	s_waitcnt lgkmcnt(1)
	v_mfma_f32_32x32x16_bf16 v[144:159], v[72:75], v[170:173], v[144:159]
	ds_read_b128 v[112:115], v234 offset:9280
	v_exp_f32_e32 v70, v118
	v_exp_f32_e32 v71, v119
	s_waitcnt lgkmcnt(1)
	v_mfma_f32_32x32x16_bf16 v[128:143], v[76:79], v[170:173], v[128:143]
	ds_read_b128 v[116:119], v234 offset:13888
	s_waitcnt vmcnt(0)
	ds_write_b128 v235, v[186:189]
	ds_write_b128 v235, v[178:181] offset:36864
	ds_write_b128 v235, v[182:185] offset:46080
	v_cvt_pk_bf16_f32 v74, v66, v67
	v_cvt_pk_bf16_f32 v75, v64, v65
	v_cvt_pk_bf16_f32 v76, v68, v69
	v_cvt_pk_bf16_f32 v77, v70, v71
	s_waitcnt lgkmcnt(4)
	v_mfma_f32_32x32x16_bf16 v[144:159], v[112:115], v[166:169], v[144:159]
	ds_read_b128 v[190:193], v234 offset:9312
	v_exp_f32_e32 v72, v120
	v_exp_f32_e32 v73, v121
	ds_read_b128 v[112:115], v234 offset:13920
	global_load_dwordx4 v[178:181], v[206:207], off
	global_load_dwordx4 v[182:185], v[208:209], off offset:256
	v_lshl_add_u64 v[214:215], v[208:209], 0, s[4:5]
	global_load_dwordx4 v[186:189], v[214:215], off offset:256
	s_waitcnt lgkmcnt(5)
	v_mfma_f32_32x32x16_bf16 v[128:143], v[116:119], v[166:169], v[128:143]
	v_exp_f32_e32 v196, v122
	v_exp_f32_e32 v197, v123
	s_waitcnt lgkmcnt(1)
	v_mfma_f32_32x32x16_bf16 v[144:159], v[190:193], v[162:165], v[144:159]
	ds_read_b128 v[116:119], v233 offset:18432
	v_exp_f32_e32 v124, v124
	v_exp_f32_e32 v125, v125
	s_waitcnt lgkmcnt(1)
	v_mfma_f32_32x32x16_bf16 v[128:143], v[112:115], v[162:165], v[128:143]
	ds_read_b128 v[120:123], v233 offset:23040
	v_exp_f32_e32 v126, v126
	v_exp_f32_e32 v127, v127
	s_waitcnt lgkmcnt(1)
	v_mfma_f32_32x32x16_bf16 v[0:15], v[116:119], v[74:77], v[0:15]
	ds_read_b128 v[112:115], v233 offset:27648
	v_cvt_pk_bf16_f32 v116, v72, v73
	v_cvt_pk_bf16_f32 v117, v196, v197
	v_cvt_pk_bf16_f32 v118, v124, v125
	v_cvt_pk_bf16_f32 v119, v126, v127
	v_exp_f32_e32 v190, v80
	v_exp_f32_e32 v191, v81
	s_waitcnt lgkmcnt(1)
	v_mfma_f32_32x32x16_bf16 v[48:63], v[120:123], v[74:77], v[48:63]
	ds_read_b128 v[78:81], v233 offset:32256
	v_exp_f32_e32 v192, v82
	v_exp_f32_e32 v193, v83
	s_waitcnt lgkmcnt(1)
	v_mfma_f32_32x32x16_bf16 v[32:47], v[112:115], v[74:77], v[32:47]
	ds_read_b128 v[120:123], v233 offset:18464
	v_exp_f32_e32 v198, v84
	v_exp_f32_e32 v199, v85
	s_waitcnt lgkmcnt(1)
	v_mfma_f32_32x32x16_bf16 v[16:31], v[78:81], v[74:77], v[16:31]
	ds_read_b128 v[82:85], v233 offset:23072
	v_exp_f32_e32 v242, v86
	v_exp_f32_e32 v243, v87
	s_waitcnt lgkmcnt(1)
	v_mfma_f32_32x32x16_bf16 v[0:15], v[120:123], v[116:119], v[0:15]
	ds_read_b128 v[74:77], v233 offset:27680
	v_cvt_pk_bf16_f32 v78, v190, v191
	v_cvt_pk_bf16_f32 v79, v192, v193
	v_cvt_pk_bf16_f32 v80, v198, v199
	v_cvt_pk_bf16_f32 v81, v242, v243
	s_waitcnt lgkmcnt(1)
	v_mfma_f32_32x32x16_bf16 v[48:63], v[82:85], v[116:119], v[48:63]
	ds_read_b128 v[112:115], v233 offset:32288
	v_exp_f32_e32 v120, v88
	v_exp_f32_e32 v121, v89
	s_waitcnt lgkmcnt(1)
	v_mfma_f32_32x32x16_bf16 v[32:47], v[74:77], v[116:119], v[32:47]
	ds_read_b128 v[82:85], v233 offset:18496
	v_exp_f32_e32 v122, v90
	v_exp_f32_e32 v123, v91
	s_waitcnt lgkmcnt(1)
	v_mfma_f32_32x32x16_bf16 v[16:31], v[112:115], v[116:119], v[16:31]
	ds_read_b128 v[74:77], v233 offset:23104
	v_exp_f32_e32 v112, v92
	v_exp_f32_e32 v113, v93
	s_waitcnt lgkmcnt(1)
	v_mfma_f32_32x32x16_bf16 v[0:15], v[82:85], v[78:81], v[0:15]
	ds_read_b128 v[86:89], v233 offset:27712
	v_exp_f32_e32 v94, v94
	v_exp_f32_e32 v95, v95
	v_cvt_pk_bf16_f32 v82, v120, v121
	v_cvt_pk_bf16_f32 v83, v122, v123
	v_cvt_pk_bf16_f32 v84, v112, v113
	v_cvt_pk_bf16_f32 v85, v94, v95
	s_waitcnt lgkmcnt(1)
	v_mfma_f32_32x32x16_bf16 v[48:63], v[74:77], v[78:81], v[48:63]
	ds_read_b128 v[90:93], v233 offset:32320
	v_add_f32_e64 v74, v124, v112
	v_add_f32_e64 v75, v125, v113
	v_add_f32_e64 v76, v126, v94
	v_add_f32_e64 v77, v127, v95
	v_pk_add_f32 v[94:95], v[196:197], v[122:123]
	v_pk_add_f32 v[72:73], v[72:73], v[120:121]
	v_pk_add_f32 v[68:69], v[68:69], v[198:199]
	v_pk_add_f32 v[112:113], v[66:67], v[190:191]
	v_pk_add_f32 v[70:71], v[70:71], v[242:243]
	v_pk_add_f32 v[114:115], v[64:65], v[192:193]
	s_waitcnt lgkmcnt(1)
	v_mfma_f32_32x32x16_bf16 v[32:47], v[86:89], v[78:81], v[32:47]
	v_add_f32_e64 v70, v114, v70
	v_add_f32_e64 v71, v115, v71
	v_add_f32_e64 v68, v112, v68
	v_add_f32_e64 v69, v113, v69
	v_add_f32_e64 v70, v94, v70
	v_add_f32_e64 v71, v95, v71
	v_pk_add_f32 v[68:69], v[72:73], v[68:69]
	ds_read_b128 v[64:67], v233 offset:18528
	v_pk_add_f32 v[70:71], v[76:77], v[70:71]
	v_pk_add_f32 v[68:69], v[74:75], v[68:69]
	s_nop 0
	v_pk_mov_b32 v[72:73], v[68:69], v[70:71] op_sel:[1,0]
	v_mov_b32_e32 v69, v71
	v_pk_add_f32 v[68:69], v[72:73], v[68:69]
	s_nop 0
	v_add_f32_e32 v68, v68, v69
	v_add_f32_e32 v237, v216, v68
	s_waitcnt lgkmcnt(1)
	v_mfma_f32_32x32x16_bf16 v[16:31], v[90:93], v[78:81], v[16:31]
	ds_read_b128 v[68:71], v233 offset:23136
	v_max3_f32 v72, v144, v145, v128
	v_max3_f32 v76, v146, v147, v129
	v_max3_f32 v77, v72, v130, v131
	s_waitcnt lgkmcnt(1)
	v_mfma_f32_32x32x16_bf16 v[0:15], v[64:67], v[82:85], v[0:15]
	ds_read_b128 v[72:75], v233 offset:27744
	v_max3_f32 v64, v77, v148, v149
	v_max3_f32 v65, v76, v150, v151
	v_max3_f32 v76, v64, v132, v133
	v_max3_f32 v77, v65, v134, v135
	s_waitcnt lgkmcnt(1)
	v_mfma_f32_32x32x16_bf16 v[48:63], v[68:71], v[82:85], v[48:63]
	ds_read_b128 v[64:67], v233 offset:32352
	v_max3_f32 v68, v76, v152, v153
	v_max3_f32 v69, v77, v154, v155
	v_max3_f32 v68, v68, v136, v137
	v_max3_f32 v69, v69, v138, v139
	s_waitcnt lgkmcnt(1)
	v_mfma_f32_32x32x16_bf16 v[32:47], v[72:75], v[82:85], v[32:47]
	v_max3_f32 v68, v68, v156, v157
	v_max3_f32 v69, v69, v158, v159
	v_max3_f32 v68, v68, v140, v141
	v_max3_f32 v69, v69, v142, v143
	s_waitcnt lgkmcnt(0)
	v_mfma_f32_32x32x16_bf16 v[16:31], v[64:67], v[82:85], v[16:31]
	v_max_f32_e32 v64, v68, v69
	v_mov_b32_e32 v65, v64
	s_nop 1
	v_permlane32_swap_b32_e32 v64, v65
	v_max_f32_e32 v64, v64, v65
	s_nop 0
	v_cmp_lt_f32_e32 vcc, s3, v64
	s_cbranch_vccz .LBB0_429
; __device__ __forceinline__ float fast_exp2(float x) { return __builtin_amdgcn_exp2f(x); }
; template <int DV, int PAR, bool KW = true, bool KL = true, bool VL = true>
; __device__ __forceinline__ void attn_iter_full(AttnState<DV>& S, int t, LAS unsigned char* lds) {
;     ...
;     if (__any(mx > 8.0f)) {
;         const float dl = fmaxf(mx, 0.f), alpha = fast_exp2(-dl);
;         S.mrun += dl; S.lsum *= alpha;
; #pragma unroll
;         for (int i = 0; i < 16; ++i) { sn0[i] -= dl; sn1[i] -= dl; S.negm[i] = -S.mrun; }
; #pragma unroll
;         for (int d = 0; d < NDB; ++d)
; #pragma unroll
;             for (int i = 0; i < 16; ++i) S.o[d][i] *= alpha;
;     }
	v_max_f32_e32 v64, v64, v64
	v_max_f32_e32 v66, 0, v64
	v_exp_f32_e64 v68, -v66
	v_add_f32_e32 v236, v236, v66
	v_xor_b32_e32 v64, 0x80000000, v236
	v_pk_add_f32 v[144:145], v[144:145], v[66:67] op_sel_hi:[1,0] neg_lo:[0,1] neg_hi:[0,1]
	v_mul_f32_e32 v237, v237, v68
	v_pk_add_f32 v[128:129], v[128:129], v[66:67] op_sel_hi:[1,0] neg_lo:[0,1] neg_hi:[0,1]
	v_pk_add_f32 v[146:147], v[146:147], v[66:67] op_sel_hi:[1,0] neg_lo:[0,1] neg_hi:[0,1]
	v_pk_add_f32 v[130:131], v[130:131], v[66:67] op_sel_hi:[1,0] neg_lo:[0,1] neg_hi:[0,1]
	v_pk_add_f32 v[148:149], v[148:149], v[66:67] op_sel_hi:[1,0] neg_lo:[0,1] neg_hi:[0,1]
	v_pk_add_f32 v[132:133], v[132:133], v[66:67] op_sel_hi:[1,0] neg_lo:[0,1] neg_hi:[0,1]
	v_pk_add_f32 v[150:151], v[150:151], v[66:67] op_sel_hi:[1,0] neg_lo:[0,1] neg_hi:[0,1]
	v_pk_add_f32 v[134:135], v[134:135], v[66:67] op_sel_hi:[1,0] neg_lo:[0,1] neg_hi:[0,1]
	v_pk_add_f32 v[152:153], v[152:153], v[66:67] op_sel_hi:[1,0] neg_lo:[0,1] neg_hi:[0,1]
	v_pk_add_f32 v[136:137], v[136:137], v[66:67] op_sel_hi:[1,0] neg_lo:[0,1] neg_hi:[0,1]
	v_pk_add_f32 v[154:155], v[154:155], v[66:67] op_sel_hi:[1,0] neg_lo:[0,1] neg_hi:[0,1]
	v_pk_add_f32 v[138:139], v[138:139], v[66:67] op_sel_hi:[1,0] neg_lo:[0,1] neg_hi:[0,1]
	v_pk_add_f32 v[156:157], v[156:157], v[66:67] op_sel_hi:[1,0] neg_lo:[0,1] neg_hi:[0,1]
	v_pk_add_f32 v[140:141], v[140:141], v[66:67] op_sel_hi:[1,0] neg_lo:[0,1] neg_hi:[0,1]
	v_pk_add_f32 v[158:159], v[158:159], v[66:67] op_sel_hi:[1,0] neg_lo:[0,1] neg_hi:[0,1]
	v_pk_add_f32 v[142:143], v[142:143], v[66:67] op_sel_hi:[1,0] neg_lo:[0,1] neg_hi:[0,1]
	v_pk_mul_f32 v[14:15], v[14:15], v[68:69] op_sel_hi:[1,0]
	v_pk_mul_f32 v[12:13], v[12:13], v[68:69] op_sel_hi:[1,0]
	v_pk_mul_f32 v[10:11], v[10:11], v[68:69] op_sel_hi:[1,0]
	v_pk_mul_f32 v[8:9], v[8:9], v[68:69] op_sel_hi:[1,0]
	v_pk_mul_f32 v[6:7], v[6:7], v[68:69] op_sel_hi:[1,0]
	v_pk_mul_f32 v[4:5], v[4:5], v[68:69] op_sel_hi:[1,0]
	v_pk_mul_f32 v[2:3], v[2:3], v[68:69] op_sel_hi:[1,0]
	v_pk_mul_f32 v[0:1], v[0:1], v[68:69] op_sel_hi:[1,0]
	v_pk_mul_f32 v[62:63], v[62:63], v[68:69] op_sel_hi:[1,0]
	v_pk_mul_f32 v[60:61], v[60:61], v[68:69] op_sel_hi:[1,0]
	v_pk_mul_f32 v[58:59], v[58:59], v[68:69] op_sel_hi:[1,0]
	v_pk_mul_f32 v[56:57], v[56:57], v[68:69] op_sel_hi:[1,0]
	v_pk_mul_f32 v[54:55], v[54:55], v[68:69] op_sel_hi:[1,0]
	v_pk_mul_f32 v[52:53], v[52:53], v[68:69] op_sel_hi:[1,0]
	v_pk_mul_f32 v[50:51], v[50:51], v[68:69] op_sel_hi:[1,0]
	v_pk_mul_f32 v[48:49], v[48:49], v[68:69] op_sel_hi:[1,0]
	v_pk_mul_f32 v[46:47], v[46:47], v[68:69] op_sel_hi:[1,0]
	v_pk_mul_f32 v[44:45], v[44:45], v[68:69] op_sel_hi:[1,0]
	v_pk_mul_f32 v[42:43], v[42:43], v[68:69] op_sel_hi:[1,0]
	v_pk_mul_f32 v[40:41], v[40:41], v[68:69] op_sel_hi:[1,0]
	v_pk_mul_f32 v[38:39], v[38:39], v[68:69] op_sel_hi:[1,0]
	v_pk_mul_f32 v[36:37], v[36:37], v[68:69] op_sel_hi:[1,0]
	v_pk_mul_f32 v[34:35], v[34:35], v[68:69] op_sel_hi:[1,0]
	v_pk_mul_f32 v[32:33], v[32:33], v[68:69] op_sel_hi:[1,0]
	v_pk_mul_f32 v[30:31], v[30:31], v[68:69] op_sel_hi:[1,0]
	v_pk_mul_f32 v[28:29], v[28:29], v[68:69] op_sel_hi:[1,0]
	v_pk_mul_f32 v[26:27], v[26:27], v[68:69] op_sel_hi:[1,0]
	v_pk_mul_f32 v[24:25], v[24:25], v[68:69] op_sel_hi:[1,0]
	v_pk_mul_f32 v[22:23], v[22:23], v[68:69] op_sel_hi:[1,0]
	v_pk_mul_f32 v[20:21], v[20:21], v[68:69] op_sel_hi:[1,0]
	v_pk_mul_f32 v[18:19], v[18:19], v[68:69] op_sel_hi:[1,0]
	v_pk_mul_f32 v[16:17], v[16:17], v[68:69] op_sel_hi:[1,0]
	v_mov_b32_e32 v65, v64
	v_mov_b32_e32 v66, v64
	v_mov_b32_e32 v67, v64
	v_mov_b32_e32 v68, v64
	v_mov_b32_e32 v69, v64
	v_mov_b32_e32 v70, v64
	v_mov_b32_e32 v71, v64
	v_mov_b32_e32 v72, v64
	v_mov_b32_e32 v73, v64
	v_mov_b32_e32 v74, v64
	v_mov_b32_e32 v75, v64
	v_mov_b32_e32 v76, v64
	v_mov_b32_e32 v77, v64
	v_mov_b32_e32 v78, v64
	v_mov_b32_e32 v79, v64
	v_mov_b32_e32 v96, v64
	v_mov_b32_e32 v97, v64
	v_mov_b32_e32 v98, v64
	v_mov_b32_e32 v99, v64
	v_mov_b32_e32 v100, v64
	v_mov_b32_e32 v101, v64
	v_mov_b32_e32 v102, v64
	v_mov_b32_e32 v103, v64
	v_mov_b32_e32 v104, v64
	v_mov_b32_e32 v105, v64
	v_mov_b32_e32 v106, v64
	v_mov_b32_e32 v107, v64
	v_mov_b32_e32 v108, v64
	v_mov_b32_e32 v109, v64
	v_mov_b32_e32 v110, v64
	v_mov_b32_e32 v111, v64
	s_branch .LBB0_430
; template <int DV, int PAR, bool KW = true, bool KL = true, bool VL = true>
; __device__ __forceinline__ void attn_iter_full(AttnState<DV>& S, int t, LAS unsigned char* lds) {
;     constexpr int NDB = DV / 32, NS = 8 + 4 * NDB, NU = 27;
;     const LAS unsigned char* BK = lds + AT_K0 + (PAR ^ 1) * AT_KB + S.koff;
;     const LAS unsigned char* BV = lds + AT_V0 + PAR * AT_VB + S.voff;
;     f32x16& C0 = PAR ? S.sd0 : S.sc0; f32x16& C1 = PAR ? S.sd1 : S.sc1; f32x16& sn0 = PAR ? S.sc0 : S.sd0; f32x16& sn1 = PAR ? S.sc1 : S.sd1;
;     sn0 = S.negm; sn1 = S.negm;
;     u32x4 pw[4]; float mxa = 0.f, mxb = 0.f, mx = 0.f; f32x16 ssum;
;     constexpr int PD = (DV == 64) ? 3 : 2; bf16x8 fr[PD + 1];
;     ...
; #pragma unroll
;     for (int i = 0; i < PD; ++i) fr[i] = AT_FRAG(i);
;     __builtin_amdgcn_sched_barrier(0);
; #pragma unroll
;     for (int i = 0; i < NS; ++i) {
;         if (i + PD < NS) fr[(i + PD) % (PD + 1)] = AT_FRAG(i + PD);
;         if (i == 3) {
;             if (KW) *(LAS u32x4*)(lds + AT_K0 + PAR * AT_KB + S.kl) = S.kreg;
;             LAS unsigned char* W = lds + AT_V0 + (PAR ^ 1) * AT_VB + S.vl; *(LAS u32x4*)W = S.vreg0; if (DV == 128) *(LAS u32x4*)(W + 64 * 144) = S.vreg1; }
;         if (i == 5) { if (KL) S.kreg = *(const u32x4*)(S.kg + (size_t)(t + 3) * 4096);
;             if (VL) { S.vreg0 = *(const u32x4*)(S.vg + (t + 2) * 64); if (DV == 128) S.vreg1 = *(const u32x4*)(S.vg + (size_t)64 * TK + (t + 2) * 64); } }
;         if (i < 8) { if (i & 1) sn1 = MFMA32(fr[i % (PD + 1)], S.qr[i >> 1], sn1); else sn0 = MFMA32(fr[i % (PD + 1)], S.qr[i >> 1], sn0); }
;         else { const int j = i - 8; S.o[j % NDB] = MFMA32(fr[i % (PD + 1)], __builtin_bit_cast(bf16x8, pw[j / NDB]), S.o[j % NDB]); }
; #pragma unroll
;         for (int u = 0; u < NU; ++u) {
;             if (u * NS / NU != i) continue;
;             if (u < 20) {
;                 const int q = u / 5, r = u % 5;
;                 if (r < 4) { const int e = 8 * q + 2 * r;
;                     if (e < 16) { C0[e] = fast_exp2(C0[e]); C0[e + 1] = fast_exp2(C0[e + 1]); }
;                     else { C1[e - 16] = fast_exp2(C1[e - 16]); C1[e - 15] = fast_exp2(C1[e - 15]); } }
;                 else { if (q < 2) { const int b0 = 8 * q; pw[q].x = pk2(C0[b0], C0[b0 + 1]); pw[q].y = pk2(C0[b0 + 2], C0[b0 + 3]); pw[q].z = pk2(C0[b0 + 4], C0[b0 + 5]); pw[q].w = pk2(C0[b0 + 6], C0[b0 + 7]); }
.LBB0_429:
.LBB0_430:
	s_barrier
	ds_read_b128 v[80:83], v234
	ds_read_b128 v[190:193], v234 offset:4608
	s_waitcnt lgkmcnt(1)
	v_mfma_f32_32x32x16_bf16 v[112:127], v[80:83], v[174:177], v[96:111]
	ds_read_b128 v[196:199], v234 offset:32
	v_exp_f32_e32 v216, v144
	v_exp_f32_e32 v217, v145
	v_exp_f32_e32 v144, v146
	v_exp_f32_e32 v145, v147
	s_waitcnt lgkmcnt(1)
	v_mfma_f32_32x32x16_bf16 v[80:95], v[190:193], v[174:177], v[96:111]
	ds_read_b128 v[242:245], v234 offset:4640
	v_exp_f32_e32 v146, v148
	v_exp_f32_e32 v147, v149
	s_waitcnt lgkmcnt(1)
	v_mfma_f32_32x32x16_bf16 v[112:127], v[196:199], v[170:173], v[112:127]
	ds_read_b128 v[190:193], v234 offset:64
	v_exp_f32_e32 v148, v150
	v_exp_f32_e32 v149, v151
	s_waitcnt lgkmcnt(1)
	v_mfma_f32_32x32x16_bf16 v[80:95], v[242:245], v[170:173], v[80:95]
	ds_read_b128 v[196:199], v234 offset:4672
	s_waitcnt vmcnt(2)
	ds_write_b128 v235, v[178:181] offset:9216
	s_waitcnt vmcnt(1)
	ds_write_b128 v235, v[182:185] offset:18432
	s_waitcnt vmcnt(0)
	ds_write_b128 v235, v[186:189] offset:27648
	v_cvt_pk_bf16_f32 v246, v216, v217
	v_cvt_pk_bf16_f32 v247, v144, v145
	v_cvt_pk_bf16_f32 v248, v146, v147
	v_cvt_pk_bf16_f32 v249, v148, v149
	s_waitcnt lgkmcnt(4)
	v_mfma_f32_32x32x16_bf16 v[112:127], v[190:193], v[166:169], v[112:127]
	ds_read_b128 v[242:245], v234 offset:96
	v_exp_f32_e32 v150, v152
	v_exp_f32_e32 v151, v153
	v_lshl_add_u64 v[152:153], v[206:207], 0, s[100:101]
	ds_read_b128 v[190:193], v234 offset:4704
	global_load_dwordx4 v[186:189], v[152:153], off
	global_load_dwordx4 v[178:181], v[208:209], off offset:384
	global_load_dwordx4 v[182:185], v[214:215], off offset:384
	s_waitcnt lgkmcnt(5)
	v_mfma_f32_32x32x16_bf16 v[80:95], v[196:199], v[166:169], v[80:95]
	v_exp_f32_e32 v210, v154
	v_exp_f32_e32 v211, v155
	s_waitcnt lgkmcnt(1)
	v_mfma_f32_32x32x16_bf16 v[112:127], v[242:245], v[162:165], v[112:127]
	ds_read_b128 v[152:155], v233 offset:36864
	v_exp_f32_e32 v212, v156
	v_exp_f32_e32 v213, v157
	s_waitcnt lgkmcnt(1)
	v_mfma_f32_32x32x16_bf16 v[80:95], v[190:193], v[162:165], v[80:95]
	ds_read_b128 v[196:199], v233 offset:41472
	v_exp_f32_e32 v214, v158
	v_exp_f32_e32 v215, v159
	s_waitcnt lgkmcnt(1)
	v_mfma_f32_32x32x16_bf16 v[0:15], v[152:155], v[246:249], v[0:15]
	ds_read_b128 v[156:159], v233 offset:46080
	v_cvt_pk_bf16_f32 v152, v150, v151
	v_cvt_pk_bf16_f32 v153, v210, v211
	v_cvt_pk_bf16_f32 v154, v212, v213
	v_cvt_pk_bf16_f32 v155, v214, v215
	v_exp_f32_e32 v242, v128
	v_exp_f32_e32 v243, v129
	s_waitcnt lgkmcnt(1)
	v_mfma_f32_32x32x16_bf16 v[48:63], v[196:199], v[246:249], v[48:63]
	ds_read_b128 v[190:193], v233 offset:50688
	v_exp_f32_e32 v196, v130
	v_exp_f32_e32 v197, v131
	s_waitcnt lgkmcnt(1)
	v_mfma_f32_32x32x16_bf16 v[32:47], v[156:159], v[246:249], v[32:47]
	ds_read_b128 v[128:131], v233 offset:36896
	v_exp_f32_e32 v198, v132
	v_exp_f32_e32 v199, v133
	s_waitcnt lgkmcnt(1)
	v_mfma_f32_32x32x16_bf16 v[16:31], v[190:193], v[246:249], v[16:31]
	ds_read_b128 v[156:159], v233 offset:41504
	v_exp_f32_e32 v244, v134
	v_exp_f32_e32 v245, v135
	s_waitcnt lgkmcnt(1)
	v_mfma_f32_32x32x16_bf16 v[0:15], v[128:131], v[152:155], v[0:15]
	ds_read_b128 v[132:135], v233 offset:46112
	v_cvt_pk_bf16_f32 v128, v242, v243
	v_cvt_pk_bf16_f32 v129, v196, v197
	v_cvt_pk_bf16_f32 v130, v198, v199
	v_cvt_pk_bf16_f32 v131, v244, v245
	s_waitcnt lgkmcnt(1)
	v_mfma_f32_32x32x16_bf16 v[48:63], v[156:159], v[152:155], v[48:63]
	ds_read_b128 v[190:193], v233 offset:50720
	v_exp_f32_e32 v246, v136
	v_exp_f32_e32 v247, v137
	s_waitcnt lgkmcnt(1)
	v_mfma_f32_32x32x16_bf16 v[32:47], v[132:135], v[152:155], v[32:47]
	ds_read_b128 v[156:159], v233 offset:36928
	v_exp_f32_e32 v248, v138
	v_exp_f32_e32 v249, v139
	s_waitcnt lgkmcnt(1)
	v_mfma_f32_32x32x16_bf16 v[16:31], v[190:193], v[152:155], v[16:31]
	ds_read_b128 v[132:135], v233 offset:41536
	v_exp_f32_e32 v190, v140
	v_exp_f32_e32 v191, v141
	s_waitcnt lgkmcnt(1)
	v_mfma_f32_32x32x16_bf16 v[0:15], v[156:159], v[128:131], v[0:15]
	ds_read_b128 v[136:139], v233 offset:46144
	v_exp_f32_e32 v156, v142
	v_exp_f32_e32 v157, v143
	v_cvt_pk_bf16_f32 v140, v246, v247
	v_cvt_pk_bf16_f32 v141, v248, v249
	v_cvt_pk_bf16_f32 v142, v190, v191
	v_cvt_pk_bf16_f32 v143, v156, v157
	s_waitcnt lgkmcnt(1)
	v_mfma_f32_32x32x16_bf16 v[48:63], v[132:135], v[128:131], v[48:63]
	ds_read_b128 v[152:155], v233 offset:50752
	v_add_f32_e64 v158, v212, v190
	v_add_f32_e64 v159, v213, v191
	v_add_f32_e64 v156, v214, v156
	v_add_f32_e64 v157, v215, v157
	v_pk_add_f32 v[190:191], v[210:211], v[248:249]
	v_pk_add_f32 v[150:151], v[150:151], v[246:247]
	v_pk_add_f32 v[146:147], v[146:147], v[198:199]
	v_pk_add_f32 v[192:193], v[216:217], v[242:243]
	v_pk_add_f32 v[148:149], v[148:149], v[244:245]
	v_pk_add_f32 v[144:145], v[144:145], v[196:197]
	s_waitcnt lgkmcnt(1)
	v_mfma_f32_32x32x16_bf16 v[32:47], v[136:139], v[128:131], v[32:47]
	v_add_f32_e64 v136, v144, v148
	v_add_f32_e64 v137, v145, v149
	v_add_f32_e64 v138, v192, v146
	v_add_f32_e64 v139, v193, v147
	v_add_f32_e64 v136, v190, v136
	v_add_f32_e64 v137, v191, v137
	v_pk_add_f32 v[138:139], v[150:151], v[138:139]
	v_pk_add_f32 v[136:137], v[156:157], v[136:137]
	v_pk_add_f32 v[138:139], v[158:159], v[138:139]
	ds_read_b128 v[132:135], v233 offset:36960
	v_pk_mov_b32 v[144:145], v[138:139], v[136:137] op_sel:[1,0]
	v_mov_b32_e32 v139, v137
	v_pk_add_f32 v[136:137], v[144:145], v[138:139]
	s_nop 0
	v_add_f32_e32 v136, v136, v137
	v_add_f32_e32 v216, v237, v136
	s_waitcnt lgkmcnt(1)
	v_mfma_f32_32x32x16_bf16 v[16:31], v[152:155], v[128:131], v[16:31]
	ds_read_b128 v[136:139], v233 offset:41568
	v_max3_f32 v128, v112, v113, v80
	v_max3_f32 v144, v114, v115, v81
	v_max3_f32 v145, v128, v82, v83
	s_waitcnt lgkmcnt(1)
	v_mfma_f32_32x32x16_bf16 v[0:15], v[132:135], v[140:143], v[0:15]
	ds_read_b128 v[128:131], v233 offset:46176
	v_max3_f32 v132, v145, v116, v117
	v_max3_f32 v133, v144, v118, v119
	v_max3_f32 v144, v132, v84, v85
	v_max3_f32 v145, v133, v86, v87
	s_waitcnt lgkmcnt(1)
	v_mfma_f32_32x32x16_bf16 v[48:63], v[136:139], v[140:143], v[48:63]
	ds_read_b128 v[132:135], v233 offset:50784
	v_max3_f32 v136, v144, v120, v121
	v_max3_f32 v137, v145, v122, v123
	v_max3_f32 v136, v136, v88, v89
	v_max3_f32 v137, v137, v90, v91
	s_waitcnt lgkmcnt(1)
	v_mfma_f32_32x32x16_bf16 v[32:47], v[128:131], v[140:143], v[32:47]
	v_max3_f32 v128, v136, v124, v125
	v_max3_f32 v129, v137, v126, v127
	v_max3_f32 v128, v128, v92, v93
	v_max3_f32 v129, v129, v94, v95
	s_waitcnt lgkmcnt(0)
	v_mfma_f32_32x32x16_bf16 v[16:31], v[132:135], v[140:143], v[16:31]
	v_max_f32_e32 v128, v128, v129
	v_mov_b32_e32 v129, v128
	s_nop 1
	v_permlane32_swap_b32_e32 v128, v129
	v_max_f32_e32 v128, v128, v129
	s_nop 0
	v_cmp_lt_f32_e32 vcc, s3, v128
	s_cbranch_vccz .LBB0_426
; __device__ __forceinline__ float fast_exp2(float x) { return __builtin_amdgcn_exp2f(x); }
; template <int DV, int PAR, bool KW = true, bool KL = true, bool VL = true>
; __device__ __forceinline__ void attn_iter_full(AttnState<DV>& S, int t, LAS unsigned char* lds) {
;     ...
;     if (__any(mx > 8.0f)) {
;         const float dl = fmaxf(mx, 0.f), alpha = fast_exp2(-dl);
;         S.mrun += dl; S.lsum *= alpha;
; #pragma unroll
;         for (int i = 0; i < 16; ++i) { sn0[i] -= dl; sn1[i] -= dl; S.negm[i] = -S.mrun; }
; #pragma unroll
;         for (int d = 0; d < NDB; ++d)
; #pragma unroll
;             for (int i = 0; i < 16; ++i) S.o[d][i] *= alpha;
;     }
	v_max_f32_e32 v64, v128, v128
	v_max_f32_e32 v65, 0, v64
	v_exp_f32_e64 v66, -v65
	v_add_f32_e32 v236, v236, v65
	v_xor_b32_e32 v64, 0x80000000, v236
	v_sub_f32_e32 v127, v127, v65
	v_mul_f32_e32 v216, v216, v66
	v_sub_f32_e32 v126, v126, v65
	v_sub_f32_e32 v125, v125, v65
	v_sub_f32_e32 v124, v124, v65
	v_sub_f32_e32 v123, v123, v65
	v_sub_f32_e32 v122, v122, v65
	v_sub_f32_e32 v121, v121, v65
	v_sub_f32_e32 v120, v120, v65
	v_sub_f32_e32 v119, v119, v65
	v_sub_f32_e32 v118, v118, v65
	v_sub_f32_e32 v117, v117, v65
	v_sub_f32_e32 v116, v116, v65
	v_sub_f32_e32 v115, v115, v65
	v_sub_f32_e32 v114, v114, v65
	v_sub_f32_e32 v113, v113, v65
	v_sub_f32_e32 v112, v112, v65
	v_sub_f32_e32 v95, v95, v65
	v_sub_f32_e32 v94, v94, v65
	v_sub_f32_e32 v93, v93, v65
	v_sub_f32_e32 v92, v92, v65
	v_sub_f32_e32 v91, v91, v65
	v_sub_f32_e32 v90, v90, v65
	v_sub_f32_e32 v89, v89, v65
	v_sub_f32_e32 v88, v88, v65
	v_sub_f32_e32 v87, v87, v65
	v_sub_f32_e32 v86, v86, v65
	v_sub_f32_e32 v85, v85, v65
	v_sub_f32_e32 v84, v84, v65
	v_sub_f32_e32 v83, v83, v65
	v_sub_f32_e32 v82, v82, v65
	v_sub_f32_e32 v81, v81, v65
	v_sub_f32_e32 v80, v80, v65
	v_pk_mul_f32 v[14:15], v[14:15], v[66:67] op_sel_hi:[1,0]
	v_pk_mul_f32 v[12:13], v[12:13], v[66:67] op_sel_hi:[1,0]
	v_pk_mul_f32 v[10:11], v[10:11], v[66:67] op_sel_hi:[1,0]
	v_pk_mul_f32 v[8:9], v[8:9], v[66:67] op_sel_hi:[1,0]
	v_pk_mul_f32 v[6:7], v[6:7], v[66:67] op_sel_hi:[1,0]
	v_pk_mul_f32 v[4:5], v[4:5], v[66:67] op_sel_hi:[1,0]
	v_pk_mul_f32 v[2:3], v[2:3], v[66:67] op_sel_hi:[1,0]
	v_pk_mul_f32 v[0:1], v[0:1], v[66:67] op_sel_hi:[1,0]
	v_pk_mul_f32 v[62:63], v[62:63], v[66:67] op_sel_hi:[1,0]
	v_pk_mul_f32 v[60:61], v[60:61], v[66:67] op_sel_hi:[1,0]
	v_pk_mul_f32 v[58:59], v[58:59], v[66:67] op_sel_hi:[1,0]
	v_pk_mul_f32 v[56:57], v[56:57], v[66:67] op_sel_hi:[1,0]
	v_pk_mul_f32 v[54:55], v[54:55], v[66:67] op_sel_hi:[1,0]
	v_pk_mul_f32 v[52:53], v[52:53], v[66:67] op_sel_hi:[1,0]
	v_pk_mul_f32 v[50:51], v[50:51], v[66:67] op_sel_hi:[1,0]
	v_pk_mul_f32 v[48:49], v[48:49], v[66:67] op_sel_hi:[1,0]
	v_pk_mul_f32 v[46:47], v[46:47], v[66:67] op_sel_hi:[1,0]
	v_pk_mul_f32 v[44:45], v[44:45], v[66:67] op_sel_hi:[1,0]
	v_pk_mul_f32 v[42:43], v[42:43], v[66:67] op_sel_hi:[1,0]
	v_pk_mul_f32 v[40:41], v[40:41], v[66:67] op_sel_hi:[1,0]
	v_pk_mul_f32 v[38:39], v[38:39], v[66:67] op_sel_hi:[1,0]
	v_pk_mul_f32 v[36:37], v[36:37], v[66:67] op_sel_hi:[1,0]
	v_pk_mul_f32 v[34:35], v[34:35], v[66:67] op_sel_hi:[1,0]
	v_pk_mul_f32 v[32:33], v[32:33], v[66:67] op_sel_hi:[1,0]
	v_pk_mul_f32 v[30:31], v[30:31], v[66:67] op_sel_hi:[1,0]
	v_pk_mul_f32 v[28:29], v[28:29], v[66:67] op_sel_hi:[1,0]
	v_pk_mul_f32 v[26:27], v[26:27], v[66:67] op_sel_hi:[1,0]
	v_pk_mul_f32 v[24:25], v[24:25], v[66:67] op_sel_hi:[1,0]
	v_pk_mul_f32 v[22:23], v[22:23], v[66:67] op_sel_hi:[1,0]
	v_pk_mul_f32 v[20:21], v[20:21], v[66:67] op_sel_hi:[1,0]
	v_pk_mul_f32 v[18:19], v[18:19], v[66:67] op_sel_hi:[1,0]
	v_pk_mul_f32 v[16:17], v[16:17], v[66:67] op_sel_hi:[1,0]
	v_mov_b32_e32 v65, v64
	v_mov_b32_e32 v66, v64
	v_mov_b32_e32 v67, v64
	v_mov_b32_e32 v68, v64
	v_mov_b32_e32 v69, v64
	v_mov_b32_e32 v70, v64
	v_mov_b32_e32 v71, v64
	v_mov_b32_e32 v72, v64
	v_mov_b32_e32 v73, v64
	v_mov_b32_e32 v74, v64
	v_mov_b32_e32 v75, v64
	v_mov_b32_e32 v76, v64
	v_mov_b32_e32 v77, v64
	v_mov_b32_e32 v78, v64
	v_mov_b32_e32 v79, v64
	v_mov_b32_e32 v96, v64
	v_mov_b32_e32 v97, v64
	v_mov_b32_e32 v98, v64
	v_mov_b32_e32 v99, v64
	v_mov_b32_e32 v100, v64
	v_mov_b32_e32 v101, v64
	v_mov_b32_e32 v102, v64
	v_mov_b32_e32 v103, v64
	v_mov_b32_e32 v104, v64
	v_mov_b32_e32 v105, v64
	v_mov_b32_e32 v106, v64
	v_mov_b32_e32 v107, v64
	v_mov_b32_e32 v108, v64
	v_mov_b32_e32 v109, v64
	v_mov_b32_e32 v110, v64
	v_mov_b32_e32 v111, v64
	s_branch .LBB0_426

; #define LAS __attribute__((address_space(3)))
; __global__ void __launch_bounds__(512, 2) fwd_megakernel(Params p) {
;     extern __shared__ __attribute__((aligned(16))) unsigned char lds_raw[];
;     LAS unsigned char* lds = (LAS unsigned char*)lds_raw;
;     cg::grid_group grid = cg::this_grid();
;     if (threadIdx.x < 16) ((LAS unsigned*)(lds + LDS_BYTES - 64))[threadIdx.x] = 0u;
;     __syncthreads();
	.amdhsa_kernel _Z14fwd_megakernel6Params
		.amdhsa_group_segment_fixed_size 0
		.amdhsa_private_segment_fixed_size 0
		.amdhsa_kernarg_size 448
		.amdhsa_user_sgpr_count 2
		.amdhsa_user_sgpr_dispatch_ptr 0
		.amdhsa_user_sgpr_queue_ptr 0
		.amdhsa_user_sgpr_kernarg_segment_ptr 1
		.amdhsa_user_sgpr_dispatch_id 0
		.amdhsa_user_sgpr_kernarg_preload_length 0
		.amdhsa_user_sgpr_kernarg_preload_offset 0
		.amdhsa_user_sgpr_private_segment_size 0
		.amdhsa_uses_dynamic_stack 0
		.amdhsa_enable_private_segment 0
		.amdhsa_system_sgpr_workgroup_id_x 1
		.amdhsa_system_sgpr_workgroup_id_y 0
		.amdhsa_system_sgpr_workgroup_id_z 0
		.amdhsa_system_sgpr_workgroup_info 0
		.amdhsa_system_vgpr_workitem_id 2
		.amdhsa_next_free_vgpr 256
		.amdhsa_next_free_sgpr 102
		.amdhsa_accum_offset 256
		.amdhsa_reserve_vcc 1
		.amdhsa_float_round_mode_32 0
		.amdhsa_float_round_mode_16_64 0
		.amdhsa_float_denorm_mode_32 3
		.amdhsa_float_denorm_mode_16_64 3
		.amdhsa_dx10_clamp 1
		.amdhsa_ieee_mode 1
		.amdhsa_fp16_overflow 0
		.amdhsa_tg_split 0
		.amdhsa_exception_fp_ieee_invalid_op 0
		.amdhsa_exception_fp_denorm_src 0
		.amdhsa_exception_fp_ieee_div_zero 0
		.amdhsa_exception_fp_ieee_overflow 0
		.amdhsa_exception_fp_ieee_underflow 0
		.amdhsa_exception_fp_ieee_inexact 0
		.amdhsa_exception_int_div_zero 0
	.end_amdhsa_kernel

; __global__ void __launch_bounds__(512, 2) fwd_megakernel(Params p) {
amdhsa.kernels:
  - .agpr_count:     0
    .args:
      - .offset:         0
        .size:           192
        .value_kind:     by_value
      - .offset:         192
        .size:           4
        .value_kind:     hidden_block_count_x
      - .offset:         196
        .size:           4
        .value_kind:     hidden_block_count_y
      - .offset:         200
        .size:           4
        .value_kind:     hidden_block_count_z
      - .offset:         204
        .size:           2
        .value_kind:     hidden_group_size_x
      - .offset:         206
        .size:           2
        .value_kind:     hidden_group_size_y
      - .offset:         208
        .size:           2
        .value_kind:     hidden_group_size_z
      - .offset:         210
        .size:           2
        .value_kind:     hidden_remainder_x
      - .offset:         212
        .size:           2
        .value_kind:     hidden_remainder_y
      - .offset:         214
        .size:           2
        .value_kind:     hidden_remainder_z
      - .offset:         232
        .size:           8
        .value_kind:     hidden_global_offset_x
      - .offset:         240
        .size:           8
        .value_kind:     hidden_global_offset_y
      - .offset:         248
        .size:           8
        .value_kind:     hidden_global_offset_z
      - .offset:         256
        .size:           2
        .value_kind:     hidden_grid_dims
      - .offset:         280
        .size:           8
        .value_kind:     hidden_multigrid_sync_arg
      - .offset:         312
        .size:           4
        .value_kind:     hidden_dynamic_lds_size
    .group_segment_fixed_size: 0
    .kernarg_segment_align: 8
    .kernarg_segment_size: 448
    .language:       OpenCL C
    .language_version:
      - 2
      - 0
    .max_flat_workgroup_size: 512
    .name:           _Z14fwd_megakernel6Params
    .private_segment_fixed_size: 0
    .sgpr_count:     108
    .sgpr_spill_count: 242
    .symbol:         _Z14fwd_megakernel6Params.kd
    .uniform_work_group_size: 1
    .uses_dynamic_stack: false
    .vgpr_count:     256
    .vgpr_spill_count: 0
    .wavefront_size: 64
